# speedup vs baseline: 1.0101x; 1.0101x over previous
.LBB0_364:
	ds_read_b128 v[138:141], v137
	ds_read_b128 v[142:145], v137 offset:1024
	ds_read_b128 v[146:149], v137 offset:2048
	ds_read_b128 v[150:153], v137 offset:3072
	s_add_u32 s64, s20, s18
	s_addc_u32 s65, s21, s19
	s_add_u32 s62, s64, 0x180
	s_addc_u32 s63, s65, 0
	s_mov_b32 m0, s42
	ds_read_b128 v[154:157], v136
	ds_read_b128 v[158:161], v136 offset:1024
	ds_read_b128 v[162:165], v136 offset:2048
	ds_read_b128 v[166:169], v136 offset:3072
	ds_read_b128 v[170:173], v136 offset:4096
	ds_read_b128 v[174:177], v136 offset:5120
	ds_read_b128 v[178:181], v136 offset:6144
	ds_read_b128 v[182:185], v136 offset:7168
	ds_read_b128 v[186:189], v137 offset:16384
	ds_read_b128 v[190:193], v137 offset:17408
	ds_read_b128 v[194:197], v137 offset:18432
	ds_read_b128 v[198:201], v137 offset:19456
	s_nop 0
	global_load_lds_dwordx4 v130, s[62:63]
	s_mov_b32 m0, s43
	s_nop 0
	global_load_lds_dwordx4 v132, s[62:63]
	s_waitcnt vmcnt(8)
	s_waitcnt lgkmcnt(0)
	s_barrier
	v_mfma_f32_16x16x32_bf16 v[30:33], v[154:157], v[138:141], v[30:33]
	v_mfma_f32_16x16x32_bf16 v[26:29], v[154:157], v[146:149], v[26:29]
	v_mfma_f32_16x16x32_bf16 v[22:25], v[162:165], v[138:141], v[22:25]
	v_mfma_f32_16x16x32_bf16 v[18:21], v[162:165], v[146:149], v[18:21]
	v_mfma_f32_16x16x32_bf16 v[14:17], v[170:173], v[138:141], v[14:17]
	v_mfma_f32_16x16x32_bf16 v[10:13], v[170:173], v[146:149], v[10:13]
	v_mfma_f32_16x16x32_bf16 v[6:9], v[178:181], v[138:141], v[6:9]
	v_mfma_f32_16x16x32_bf16 v[2:5], v[178:181], v[146:149], v[2:5]
	v_mfma_f32_16x16x32_bf16 v[30:33], v[158:161], v[142:145], v[30:33]
	v_mfma_f32_16x16x32_bf16 v[26:29], v[158:161], v[150:153], v[26:29]
	v_mfma_f32_16x16x32_bf16 v[22:25], v[166:169], v[142:145], v[22:25]
	v_mfma_f32_16x16x32_bf16 v[18:21], v[166:169], v[150:153], v[18:21]
	v_mfma_f32_16x16x32_bf16 v[14:17], v[174:177], v[142:145], v[14:17]
	v_mfma_f32_16x16x32_bf16 v[10:13], v[174:177], v[150:153], v[10:13]
	v_mfma_f32_16x16x32_bf16 v[6:9], v[182:185], v[142:145], v[6:9]
	v_mfma_f32_16x16x32_bf16 v[2:5], v[182:185], v[150:153], v[2:5]
	v_mfma_f32_16x16x32_bf16 v[62:65], v[154:157], v[186:189], v[62:65]
	v_mfma_f32_16x16x32_bf16 v[58:61], v[154:157], v[194:197], v[58:61]
	v_mfma_f32_16x16x32_bf16 v[54:57], v[162:165], v[186:189], v[54:57]
	v_mfma_f32_16x16x32_bf16 v[50:53], v[162:165], v[194:197], v[50:53]
	v_mfma_f32_16x16x32_bf16 v[46:49], v[170:173], v[186:189], v[46:49]
	v_mfma_f32_16x16x32_bf16 v[42:45], v[170:173], v[194:197], v[42:45]
	v_mfma_f32_16x16x32_bf16 v[38:41], v[178:181], v[186:189], v[38:41]
	v_mfma_f32_16x16x32_bf16 v[34:37], v[178:181], v[194:197], v[34:37]
	v_mfma_f32_16x16x32_bf16 v[62:65], v[158:161], v[190:193], v[62:65]
	v_mfma_f32_16x16x32_bf16 v[58:61], v[158:161], v[198:201], v[58:61]
	v_mfma_f32_16x16x32_bf16 v[54:57], v[166:169], v[190:193], v[54:57]
	v_mfma_f32_16x16x32_bf16 v[50:53], v[166:169], v[198:201], v[50:53]
	v_mfma_f32_16x16x32_bf16 v[46:49], v[174:177], v[190:193], v[46:49]
	v_mfma_f32_16x16x32_bf16 v[42:45], v[174:177], v[198:201], v[42:45]
	v_mfma_f32_16x16x32_bf16 v[38:41], v[182:185], v[190:193], v[38:41]
	v_mfma_f32_16x16x32_bf16 v[34:37], v[182:185], v[198:201], v[34:37]
	s_barrier
	ds_read_b128 v[154:157], v136 offset:16384
	ds_read_b128 v[158:161], v136 offset:17408
	ds_read_b128 v[162:165], v136 offset:18432
	ds_read_b128 v[166:169], v136 offset:19456
	ds_read_b128 v[170:173], v136 offset:20480
	ds_read_b128 v[174:177], v136 offset:21504
	ds_read_b128 v[178:181], v136 offset:22528
	ds_read_b128 v[182:185], v136 offset:23552
	s_add_u32 s66, s56, s18
	s_addc_u32 s67, s57, s19
	s_add_u32 s62, s66, 0x200
	s_addc_u32 s63, s67, 0
	s_mov_b32 m0, s28
	s_nop 0
	global_load_lds_dwordx4 v130, s[62:63]
	s_mov_b32 m0, s29
	s_nop 0
	global_load_lds_dwordx4 v132, s[62:63]
	s_add_u32 s68, s17, s18
	s_addc_u32 s69, s58, s19
	s_add_u32 s62, s68, 0x200
	s_addc_u32 s63, s69, 0
	s_mov_b32 m0, s27
	s_nop 0
	global_load_lds_dwordx4 v130, s[62:63]
	s_mov_b32 m0, s30
	s_nop 0
	global_load_lds_dwordx4 v132, s[62:63]
	s_add_u32 s70, s59, s18
	s_addc_u32 s71, s60, s19
	s_add_u32 s62, s70, 0x200
	s_addc_u32 s63, s71, 0
	s_mov_b32 m0, s31
	s_nop 0
	global_load_lds_dwordx4 v130, s[62:63]
	s_mov_b32 m0, s33
	s_nop 0
	global_load_lds_dwordx4 v132, s[62:63]
	s_waitcnt vmcnt(8)
	s_waitcnt lgkmcnt(0)
	s_barrier
	v_mfma_f32_16x16x32_bf16 v[94:97], v[154:157], v[138:141], v[94:97]
	v_mfma_f32_16x16x32_bf16 v[90:93], v[154:157], v[146:149], v[90:93]
	v_mfma_f32_16x16x32_bf16 v[86:89], v[162:165], v[138:141], v[86:89]
	v_mfma_f32_16x16x32_bf16 v[82:85], v[162:165], v[146:149], v[82:85]
	v_mfma_f32_16x16x32_bf16 v[78:81], v[170:173], v[138:141], v[78:81]
	v_mfma_f32_16x16x32_bf16 v[74:77], v[170:173], v[146:149], v[74:77]
	v_mfma_f32_16x16x32_bf16 v[70:73], v[178:181], v[138:141], v[70:73]
	v_mfma_f32_16x16x32_bf16 v[66:69], v[178:181], v[146:149], v[66:69]
	v_mfma_f32_16x16x32_bf16 v[94:97], v[158:161], v[142:145], v[94:97]
	v_mfma_f32_16x16x32_bf16 v[90:93], v[158:161], v[150:153], v[90:93]
	v_mfma_f32_16x16x32_bf16 v[86:89], v[166:169], v[142:145], v[86:89]
	v_mfma_f32_16x16x32_bf16 v[82:85], v[166:169], v[150:153], v[82:85]
	v_mfma_f32_16x16x32_bf16 v[78:81], v[174:177], v[142:145], v[78:81]
	v_mfma_f32_16x16x32_bf16 v[74:77], v[174:177], v[150:153], v[74:77]
	v_mfma_f32_16x16x32_bf16 v[70:73], v[182:185], v[142:145], v[70:73]
	v_mfma_f32_16x16x32_bf16 v[66:69], v[182:185], v[150:153], v[66:69]
	v_mfma_f32_16x16x32_bf16 v[126:129], v[154:157], v[186:189], v[126:129]
	v_mfma_f32_16x16x32_bf16 v[122:125], v[154:157], v[194:197], v[122:125]
	v_mfma_f32_16x16x32_bf16 v[118:121], v[162:165], v[186:189], v[118:121]
	v_mfma_f32_16x16x32_bf16 v[114:117], v[162:165], v[194:197], v[114:117]
	v_mfma_f32_16x16x32_bf16 v[110:113], v[170:173], v[186:189], v[110:113]
	v_mfma_f32_16x16x32_bf16 v[106:109], v[170:173], v[194:197], v[106:109]
	v_mfma_f32_16x16x32_bf16 v[102:105], v[178:181], v[186:189], v[102:105]
	v_mfma_f32_16x16x32_bf16 v[98:101], v[178:181], v[194:197], v[98:101]
	v_mfma_f32_16x16x32_bf16 v[126:129], v[158:161], v[190:193], v[126:129]
	v_mfma_f32_16x16x32_bf16 v[122:125], v[158:161], v[198:201], v[122:125]
	v_mfma_f32_16x16x32_bf16 v[118:121], v[166:169], v[190:193], v[118:121]
	v_mfma_f32_16x16x32_bf16 v[114:117], v[166:169], v[198:201], v[114:117]
	v_mfma_f32_16x16x32_bf16 v[110:113], v[174:177], v[190:193], v[110:113]
	v_mfma_f32_16x16x32_bf16 v[106:109], v[174:177], v[198:201], v[106:109]
	v_mfma_f32_16x16x32_bf16 v[102:105], v[182:185], v[190:193], v[102:105]
	v_mfma_f32_16x16x32_bf16 v[98:101], v[182:185], v[198:201], v[98:101]
	s_barrier
	ds_read_b128 v[138:141], v137 offset:32768
	ds_read_b128 v[142:145], v137 offset:33792
	ds_read_b128 v[146:149], v137 offset:34816
	ds_read_b128 v[150:153], v137 offset:35840
	s_add_u32 s62, s64, 0x200
	s_addc_u32 s63, s65, 0
	s_mov_b32 m0, s34
	ds_read_b128 v[154:157], v136 offset:32768
	ds_read_b128 v[158:161], v136 offset:33792
	ds_read_b128 v[162:165], v136 offset:34816
	ds_read_b128 v[166:169], v136 offset:35840
	ds_read_b128 v[170:173], v136 offset:36864
	ds_read_b128 v[174:177], v136 offset:37888
	ds_read_b128 v[178:181], v136 offset:38912
	ds_read_b128 v[182:185], v136 offset:39936
	ds_read_b128 v[186:189], v137 offset:49152
	ds_read_b128 v[190:193], v137 offset:50176
	ds_read_b128 v[194:197], v137 offset:51200
	ds_read_b128 v[198:201], v137 offset:52224
	s_nop 0
	global_load_lds_dwordx4 v130, s[62:63]
	s_mov_b32 m0, s35
	s_nop 0
	global_load_lds_dwordx4 v132, s[62:63]
	s_waitcnt vmcnt(8)
	s_waitcnt lgkmcnt(0)
	s_barrier
	v_mfma_f32_16x16x32_bf16 v[30:33], v[154:157], v[138:141], v[30:33]
	v_mfma_f32_16x16x32_bf16 v[26:29], v[154:157], v[146:149], v[26:29]
	v_mfma_f32_16x16x32_bf16 v[22:25], v[162:165], v[138:141], v[22:25]
	v_mfma_f32_16x16x32_bf16 v[18:21], v[162:165], v[146:149], v[18:21]
	v_mfma_f32_16x16x32_bf16 v[14:17], v[170:173], v[138:141], v[14:17]
	v_mfma_f32_16x16x32_bf16 v[10:13], v[170:173], v[146:149], v[10:13]
	v_mfma_f32_16x16x32_bf16 v[6:9], v[178:181], v[138:141], v[6:9]
	v_mfma_f32_16x16x32_bf16 v[2:5], v[178:181], v[146:149], v[2:5]
	v_mfma_f32_16x16x32_bf16 v[30:33], v[158:161], v[142:145], v[30:33]
	v_mfma_f32_16x16x32_bf16 v[26:29], v[158:161], v[150:153], v[26:29]
	v_mfma_f32_16x16x32_bf16 v[22:25], v[166:169], v[142:145], v[22:25]
	v_mfma_f32_16x16x32_bf16 v[18:21], v[166:169], v[150:153], v[18:21]
	v_mfma_f32_16x16x32_bf16 v[14:17], v[174:177], v[142:145], v[14:17]
	v_mfma_f32_16x16x32_bf16 v[10:13], v[174:177], v[150:153], v[10:13]
	v_mfma_f32_16x16x32_bf16 v[6:9], v[182:185], v[142:145], v[6:9]
	v_mfma_f32_16x16x32_bf16 v[2:5], v[182:185], v[150:153], v[2:5]
	v_mfma_f32_16x16x32_bf16 v[62:65], v[154:157], v[186:189], v[62:65]
	v_mfma_f32_16x16x32_bf16 v[58:61], v[154:157], v[194:197], v[58:61]
	v_mfma_f32_16x16x32_bf16 v[54:57], v[162:165], v[186:189], v[54:57]
	v_mfma_f32_16x16x32_bf16 v[50:53], v[162:165], v[194:197], v[50:53]
	v_mfma_f32_16x16x32_bf16 v[46:49], v[170:173], v[186:189], v[46:49]
	v_mfma_f32_16x16x32_bf16 v[42:45], v[170:173], v[194:197], v[42:45]
	v_mfma_f32_16x16x32_bf16 v[38:41], v[178:181], v[186:189], v[38:41]
	v_mfma_f32_16x16x32_bf16 v[34:37], v[178:181], v[194:197], v[34:37]
	v_mfma_f32_16x16x32_bf16 v[62:65], v[158:161], v[190:193], v[62:65]
	v_mfma_f32_16x16x32_bf16 v[58:61], v[158:161], v[198:201], v[58:61]
	v_mfma_f32_16x16x32_bf16 v[54:57], v[166:169], v[190:193], v[54:57]
	v_mfma_f32_16x16x32_bf16 v[50:53], v[166:169], v[198:201], v[50:53]
	v_mfma_f32_16x16x32_bf16 v[46:49], v[174:177], v[190:193], v[46:49]
	v_mfma_f32_16x16x32_bf16 v[42:45], v[174:177], v[198:201], v[42:45]
	v_mfma_f32_16x16x32_bf16 v[38:41], v[182:185], v[190:193], v[38:41]
	v_mfma_f32_16x16x32_bf16 v[34:37], v[182:185], v[198:201], v[34:37]
	s_barrier
	ds_read_b128 v[154:157], v136 offset:49152
	ds_read_b128 v[158:161], v136 offset:50176
	ds_read_b128 v[162:165], v136 offset:51200
	ds_read_b128 v[166:169], v136 offset:52224
	ds_read_b128 v[170:173], v136 offset:53248
	ds_read_b128 v[174:177], v136 offset:54272
	ds_read_b128 v[178:181], v136 offset:55296
	ds_read_b128 v[182:185], v136 offset:56320
	s_add_u32 s62, s66, 0x280
	s_addc_u32 s63, s67, 0
	s_mov_b32 m0, s36
	s_nop 0
	global_load_lds_dwordx4 v130, s[62:63]
	s_mov_b32 m0, s37
	s_nop 0
	global_load_lds_dwordx4 v132, s[62:63]
	s_add_u32 s62, s68, 0x280
	s_addc_u32 s63, s69, 0
	s_mov_b32 m0, s38
	s_nop 0
	global_load_lds_dwordx4 v130, s[62:63]
	s_mov_b32 m0, s39
	s_nop 0
	global_load_lds_dwordx4 v132, s[62:63]
	s_add_u32 s62, s70, 0x280
	s_addc_u32 s63, s71, 0
	s_mov_b32 m0, s40
	s_nop 0
	global_load_lds_dwordx4 v130, s[62:63]
	s_mov_b32 m0, s41
	s_nop 0
	global_load_lds_dwordx4 v132, s[62:63]
	s_waitcnt vmcnt(8)
	s_waitcnt lgkmcnt(0)
	s_barrier
	v_mfma_f32_16x16x32_bf16 v[94:97], v[154:157], v[138:141], v[94:97]
	v_mfma_f32_16x16x32_bf16 v[90:93], v[154:157], v[146:149], v[90:93]
	v_mfma_f32_16x16x32_bf16 v[86:89], v[162:165], v[138:141], v[86:89]
	v_mfma_f32_16x16x32_bf16 v[82:85], v[162:165], v[146:149], v[82:85]
	v_mfma_f32_16x16x32_bf16 v[78:81], v[170:173], v[138:141], v[78:81]
	v_mfma_f32_16x16x32_bf16 v[74:77], v[170:173], v[146:149], v[74:77]
	v_mfma_f32_16x16x32_bf16 v[70:73], v[178:181], v[138:141], v[70:73]
	v_mfma_f32_16x16x32_bf16 v[66:69], v[178:181], v[146:149], v[66:69]
	v_mfma_f32_16x16x32_bf16 v[94:97], v[158:161], v[142:145], v[94:97]
	v_mfma_f32_16x16x32_bf16 v[90:93], v[158:161], v[150:153], v[90:93]
	v_mfma_f32_16x16x32_bf16 v[86:89], v[166:169], v[142:145], v[86:89]
	v_mfma_f32_16x16x32_bf16 v[82:85], v[166:169], v[150:153], v[82:85]
	v_mfma_f32_16x16x32_bf16 v[78:81], v[174:177], v[142:145], v[78:81]
	v_mfma_f32_16x16x32_bf16 v[74:77], v[174:177], v[150:153], v[74:77]
	v_mfma_f32_16x16x32_bf16 v[70:73], v[182:185], v[142:145], v[70:73]
	v_mfma_f32_16x16x32_bf16 v[66:69], v[182:185], v[150:153], v[66:69]
	v_mfma_f32_16x16x32_bf16 v[126:129], v[154:157], v[186:189], v[126:129]
	v_mfma_f32_16x16x32_bf16 v[122:125], v[154:157], v[194:197], v[122:125]
	v_mfma_f32_16x16x32_bf16 v[118:121], v[162:165], v[186:189], v[118:121]
	v_mfma_f32_16x16x32_bf16 v[114:117], v[162:165], v[194:197], v[114:117]
	v_mfma_f32_16x16x32_bf16 v[110:113], v[170:173], v[186:189], v[110:113]
	v_mfma_f32_16x16x32_bf16 v[106:109], v[170:173], v[194:197], v[106:109]
	v_mfma_f32_16x16x32_bf16 v[102:105], v[178:181], v[186:189], v[102:105]
	v_mfma_f32_16x16x32_bf16 v[98:101], v[178:181], v[194:197], v[98:101]
	v_mfma_f32_16x16x32_bf16 v[126:129], v[158:161], v[190:193], v[126:129]
	v_mfma_f32_16x16x32_bf16 v[122:125], v[158:161], v[198:201], v[122:125]
	v_mfma_f32_16x16x32_bf16 v[118:121], v[166:169], v[190:193], v[118:121]
	v_mfma_f32_16x16x32_bf16 v[114:117], v[166:169], v[198:201], v[114:117]
	v_mfma_f32_16x16x32_bf16 v[110:113], v[174:177], v[190:193], v[110:113]
	v_mfma_f32_16x16x32_bf16 v[106:109], v[174:177], v[198:201], v[106:109]
	v_mfma_f32_16x16x32_bf16 v[102:105], v[182:185], v[190:193], v[102:105]
	v_mfma_f32_16x16x32_bf16 v[98:101], v[182:185], v[198:201], v[98:101]
	s_add_i32 s61, s61, 2
	s_add_u32 s18, s18, 0x100
	s_addc_u32 s19, s19, 0
	s_cmp_gt_u32 s61, 11
	s_barrier
	s_cbranch_scc0 .LBB0_364
	s_lshl_b64 s[14:15], s[14:15], 1
	s_add_u32 s14, s44, s14
	s_addc_u32 s15, s45, s15
	s_mov_b32 m0, s42
	ds_read_b128 v[142:145], v137
	ds_read_b128 v[146:149], v137 offset:1024
	ds_read_b128 v[150:153], v137 offset:2048
	ds_read_b128 v[154:157], v137 offset:3072
	ds_read_b128 v[158:161], v136
	ds_read_b128 v[162:165], v136 offset:1024
	ds_read_b128 v[166:169], v136 offset:2048
	ds_read_b128 v[170:173], v136 offset:3072
	ds_read_b128 v[174:177], v136 offset:4096
	ds_read_b128 v[178:181], v136 offset:5120
	ds_read_b128 v[182:185], v136 offset:6144
	ds_read_b128 v[186:189], v136 offset:7168
	s_nop 0
	global_load_lds_dwordx4 v130, s[14:15]
	s_mov_b32 m0, s43
	s_nop 0
	global_load_lds_dwordx4 v132, s[14:15]
	s_waitcnt vmcnt(8)
	s_barrier
	s_waitcnt lgkmcnt(0)
	s_setprio 3
	s_waitcnt lgkmcnt(0)
	v_mfma_f32_16x16x32_bf16 v[30:33], v[158:161], v[142:145], v[30:33]
	v_mfma_f32_16x16x32_bf16 v[26:29], v[158:161], v[150:153], v[26:29]
	v_mfma_f32_16x16x32_bf16 v[22:25], v[166:169], v[142:145], v[22:25]
	v_mfma_f32_16x16x32_bf16 v[18:21], v[166:169], v[150:153], v[18:21]
	v_mfma_f32_16x16x32_bf16 v[14:17], v[174:177], v[142:145], v[14:17]
	v_mfma_f32_16x16x32_bf16 v[10:13], v[174:177], v[150:153], v[10:13]
	v_mfma_f32_16x16x32_bf16 v[6:9], v[182:185], v[142:145], v[6:9]
	v_mfma_f32_16x16x32_bf16 v[2:5], v[182:185], v[150:153], v[2:5]
	v_mfma_f32_16x16x32_bf16 v[30:33], v[162:165], v[146:149], v[30:33]
	v_mfma_f32_16x16x32_bf16 v[26:29], v[162:165], v[154:157], v[26:29]
	v_mfma_f32_16x16x32_bf16 v[22:25], v[170:173], v[146:149], v[22:25]
	v_mfma_f32_16x16x32_bf16 v[18:21], v[170:173], v[154:157], v[18:21]
	v_mfma_f32_16x16x32_bf16 v[14:17], v[178:181], v[146:149], v[14:17]
	v_mfma_f32_16x16x32_bf16 v[10:13], v[178:181], v[154:157], v[10:13]
	v_mfma_f32_16x16x32_bf16 v[6:9], v[186:189], v[146:149], v[6:9]
	v_mfma_f32_16x16x32_bf16 v[2:5], v[186:189], v[154:157], v[2:5]
	s_setprio 0
	s_barrier
	ds_read_b128 v[190:193], v137 offset:16384
	ds_read_b128 v[194:197], v137 offset:17408
	ds_read_b128 v[198:201], v137 offset:18432
	ds_read_b128 v[202:205], v137 offset:19456
	s_barrier
	s_waitcnt lgkmcnt(0)
	s_setprio 3
	s_waitcnt lgkmcnt(0)
	v_mfma_f32_16x16x32_bf16 v[62:65], v[158:161], v[190:193], v[62:65]
	v_mfma_f32_16x16x32_bf16 v[58:61], v[158:161], v[198:201], v[58:61]
	v_mfma_f32_16x16x32_bf16 v[54:57], v[166:169], v[190:193], v[54:57]
	v_mfma_f32_16x16x32_bf16 v[50:53], v[166:169], v[198:201], v[50:53]
	v_mfma_f32_16x16x32_bf16 v[46:49], v[174:177], v[190:193], v[46:49]
	v_mfma_f32_16x16x32_bf16 v[42:45], v[174:177], v[198:201], v[42:45]
	v_mfma_f32_16x16x32_bf16 v[38:41], v[182:185], v[190:193], v[38:41]
	v_mfma_f32_16x16x32_bf16 v[34:37], v[182:185], v[198:201], v[34:37]
	v_mfma_f32_16x16x32_bf16 v[62:65], v[162:165], v[194:197], v[62:65]
	v_mfma_f32_16x16x32_bf16 v[58:61], v[162:165], v[202:205], v[58:61]
	v_mfma_f32_16x16x32_bf16 v[54:57], v[170:173], v[194:197], v[54:57]
	v_mfma_f32_16x16x32_bf16 v[50:53], v[170:173], v[202:205], v[50:53]
	v_mfma_f32_16x16x32_bf16 v[46:49], v[178:181], v[194:197], v[46:49]
	v_mfma_f32_16x16x32_bf16 v[42:45], v[178:181], v[202:205], v[42:45]
	v_mfma_f32_16x16x32_bf16 v[38:41], v[186:189], v[194:197], v[38:41]
	v_mfma_f32_16x16x32_bf16 v[34:37], v[186:189], v[202:205], v[34:37]
	s_setprio 0
	s_barrier
	ds_read_b128 v[158:161], v136 offset:16384
	ds_read_b128 v[162:165], v136 offset:17408
	ds_read_b128 v[166:169], v136 offset:18432
	ds_read_b128 v[170:173], v136 offset:19456
	ds_read_b128 v[174:177], v136 offset:20480
	ds_read_b128 v[178:181], v136 offset:21504
	ds_read_b128 v[182:185], v136 offset:22528
	ds_read_b128 v[186:189], v136 offset:23552
	s_waitcnt vmcnt(4)
	s_barrier
	s_waitcnt lgkmcnt(0)
	s_setprio 3
	s_waitcnt lgkmcnt(0)
	v_mfma_f32_16x16x32_bf16 v[94:97], v[158:161], v[142:145], v[94:97]
	v_mfma_f32_16x16x32_bf16 v[90:93], v[158:161], v[150:153], v[90:93]
	v_mfma_f32_16x16x32_bf16 v[86:89], v[166:169], v[142:145], v[86:89]
	v_mfma_f32_16x16x32_bf16 v[82:85], v[166:169], v[150:153], v[82:85]
	v_mfma_f32_16x16x32_bf16 v[78:81], v[174:177], v[142:145], v[78:81]
	v_mfma_f32_16x16x32_bf16 v[74:77], v[174:177], v[150:153], v[74:77]
	v_mfma_f32_16x16x32_bf16 v[70:73], v[182:185], v[142:145], v[70:73]
	v_mfma_f32_16x16x32_bf16 v[66:69], v[182:185], v[150:153], v[66:69]
	v_mfma_f32_16x16x32_bf16 v[212:215], v[162:165], v[146:149], v[94:97]
	v_mfma_f32_16x16x32_bf16 v[216:219], v[162:165], v[154:157], v[90:93]
	v_mfma_f32_16x16x32_bf16 v[220:223], v[170:173], v[146:149], v[86:89]
	v_mfma_f32_16x16x32_bf16 v[224:227], v[170:173], v[154:157], v[82:85]
	v_mfma_f32_16x16x32_bf16 v[228:231], v[178:181], v[146:149], v[78:81]
	v_mfma_f32_16x16x32_bf16 v[232:235], v[178:181], v[154:157], v[74:77]
	v_mfma_f32_16x16x32_bf16 v[142:145], v[186:189], v[146:149], v[70:73]
	v_mfma_f32_16x16x32_bf16 v[146:149], v[186:189], v[154:157], v[66:69]
	s_setprio 0
	s_setprio 3
	v_mfma_f32_16x16x32_bf16 v[66:69], v[158:161], v[190:193], v[126:129]
	v_mfma_f32_16x16x32_bf16 v[150:153], v[162:165], v[194:197], v[66:69]
	v_mfma_f32_16x16x32_bf16 v[66:69], v[158:161], v[198:201], v[122:125]
	v_mfma_f32_16x16x32_bf16 v[154:157], v[162:165], v[202:205], v[66:69]
	v_mfma_f32_16x16x32_bf16 v[66:69], v[166:169], v[190:193], v[118:121]
	v_mfma_f32_16x16x32_bf16 v[158:161], v[170:173], v[194:197], v[66:69]
	v_mfma_f32_16x16x32_bf16 v[66:69], v[166:169], v[198:201], v[114:117]
	v_mfma_f32_16x16x32_bf16 v[162:165], v[170:173], v[202:205], v[66:69]
	v_mfma_f32_16x16x32_bf16 v[66:69], v[174:177], v[190:193], v[110:113]
	v_mfma_f32_16x16x32_bf16 v[166:169], v[178:181], v[194:197], v[66:69]
	v_mfma_f32_16x16x32_bf16 v[66:69], v[174:177], v[198:201], v[106:109]
	v_mfma_f32_16x16x32_bf16 v[170:173], v[178:181], v[202:205], v[66:69]
	v_mfma_f32_16x16x32_bf16 v[66:69], v[182:185], v[190:193], v[102:105]
	v_mfma_f32_16x16x32_bf16 v[174:177], v[186:189], v[194:197], v[66:69]
	v_mfma_f32_16x16x32_bf16 v[66:69], v[182:185], v[198:201], v[98:101]
	v_mfma_f32_16x16x32_bf16 v[178:181], v[186:189], v[202:205], v[66:69]
	s_setprio 0
	s_barrier
	ds_read_b128 v[182:185], v137 offset:32768
	ds_read_b128 v[186:189], v137 offset:33792
	ds_read_b128 v[190:193], v137 offset:34816
	ds_read_b128 v[194:197], v137 offset:35840
	s_nop 0
	ds_read_b128 v[66:69], v136 offset:32768
	ds_read_b128 v[70:73], v136 offset:33792
	ds_read_b128 v[82:85], v136 offset:34816
	ds_read_b128 v[86:89], v136 offset:35840
	ds_read_b128 v[198:201], v136 offset:36864
	ds_read_b128 v[202:205], v136 offset:37888
	ds_read_b128 v[236:239], v136 offset:38912
	ds_read_b128 v[240:243], v136 offset:39936
	s_waitcnt vmcnt(2)
	s_barrier
	s_waitcnt lgkmcnt(0)
	s_setprio 3
	s_waitcnt lgkmcnt(0)
	v_mfma_f32_16x16x32_bf16 v[30:33], v[66:69], v[182:185], v[30:33]
	v_mfma_f32_16x16x32_bf16 v[26:29], v[66:69], v[190:193], v[26:29]
	v_mfma_f32_16x16x32_bf16 v[22:25], v[82:85], v[182:185], v[22:25]
	v_mfma_f32_16x16x32_bf16 v[18:21], v[82:85], v[190:193], v[18:21]
	v_mfma_f32_16x16x32_bf16 v[14:17], v[198:201], v[182:185], v[14:17]
	v_mfma_f32_16x16x32_bf16 v[10:13], v[198:201], v[190:193], v[10:13]
	v_mfma_f32_16x16x32_bf16 v[6:9], v[236:239], v[182:185], v[6:9]
	v_mfma_f32_16x16x32_bf16 v[2:5], v[236:239], v[190:193], v[2:5]
	v_mfma_f32_16x16x32_bf16 v[122:125], v[70:73], v[186:189], v[30:33]
	v_mfma_f32_16x16x32_bf16 v[126:129], v[70:73], v[194:197], v[26:29]
	v_mfma_f32_16x16x32_bf16 v[106:109], v[86:89], v[186:189], v[22:25]
	v_mfma_f32_16x16x32_bf16 v[110:113], v[86:89], v[194:197], v[18:21]
	v_mfma_f32_16x16x32_bf16 v[90:93], v[202:205], v[186:189], v[14:17]
	v_mfma_f32_16x16x32_bf16 v[94:97], v[202:205], v[194:197], v[10:13]
	v_mfma_f32_16x16x32_bf16 v[74:77], v[240:243], v[186:189], v[6:9]
	v_mfma_f32_16x16x32_bf16 v[78:81], v[240:243], v[194:197], v[2:5]
	s_setprio 0
	s_barrier
	s_nop 0
	ds_read_b128 v[2:5], v137 offset:49152
	ds_read_b128 v[6:9], v137 offset:50176
	ds_read_b128 v[244:247], v137 offset:51200
	ds_read_b128 v[248:251], v137 offset:52224
	s_waitcnt vmcnt(0)
	s_barrier
	s_waitcnt lgkmcnt(0)
	s_setprio 3
	s_waitcnt lgkmcnt(0)
	v_mfma_f32_16x16x32_bf16 v[10:13], v[66:69], v[2:5], v[62:65]
	v_mfma_f32_16x16x32_bf16 v[114:117], v[70:73], v[6:9], v[10:13]
	v_mfma_f32_16x16x32_bf16 v[10:13], v[66:69], v[244:247], v[58:61]
	v_mfma_f32_16x16x32_bf16 v[118:121], v[70:73], v[248:251], v[10:13]
	v_mfma_f32_16x16x32_bf16 v[10:13], v[82:85], v[2:5], v[54:57]
	v_mfma_f32_16x16x32_bf16 v[98:101], v[86:89], v[6:9], v[10:13]
	v_mfma_f32_16x16x32_bf16 v[10:13], v[82:85], v[244:247], v[50:53]
	v_mfma_f32_16x16x32_bf16 v[102:105], v[86:89], v[248:251], v[10:13]
	v_mfma_f32_16x16x32_bf16 v[10:13], v[198:201], v[2:5], v[46:49]
	v_mfma_f32_16x16x32_bf16 v[82:85], v[202:205], v[6:9], v[10:13]
	v_mfma_f32_16x16x32_bf16 v[10:13], v[198:201], v[244:247], v[42:45]
	v_mfma_f32_16x16x32_bf16 v[86:89], v[202:205], v[248:251], v[10:13]
	v_mfma_f32_16x16x32_bf16 v[10:13], v[236:239], v[2:5], v[38:41]
	v_mfma_f32_16x16x32_bf16 v[66:69], v[240:243], v[6:9], v[10:13]
	v_mfma_f32_16x16x32_bf16 v[10:13], v[236:239], v[244:247], v[34:37]
	v_mfma_f32_16x16x32_bf16 v[70:73], v[240:243], v[248:251], v[10:13]
	s_setprio 0
	s_barrier
	ds_read_b128 v[18:21], v136 offset:49152
	ds_read_b128 v[22:25], v136 offset:50176
	ds_read_b128 v[38:41], v136 offset:51200
	ds_read_b128 v[198:201], v136 offset:52224
	ds_read_b128 v[202:205], v136 offset:53248
	ds_read_b128 v[236:239], v136 offset:54272
	ds_read_b128 v[240:243], v136 offset:55296
	ds_read_b128 v[138:141], v136 offset:56320
	s_barrier
	s_waitcnt lgkmcnt(0)
	s_setprio 3
	s_waitcnt lgkmcnt(0)
	v_mfma_f32_16x16x32_bf16 v[10:13], v[18:21], v[182:185], v[212:215]
	v_mfma_f32_16x16x32_bf16 v[58:61], v[22:25], v[186:189], v[10:13]
	v_mfma_f32_16x16x32_bf16 v[10:13], v[18:21], v[190:193], v[216:219]
	v_mfma_f32_16x16x32_bf16 v[62:65], v[22:25], v[194:197], v[10:13]
	v_mfma_f32_16x16x32_bf16 v[10:13], v[38:41], v[182:185], v[220:223]
	v_mfma_f32_16x16x32_bf16 v[42:45], v[198:201], v[186:189], v[10:13]
	v_mfma_f32_16x16x32_bf16 v[10:13], v[38:41], v[190:193], v[224:227]
	v_mfma_f32_16x16x32_bf16 v[46:49], v[198:201], v[194:197], v[10:13]
	v_mfma_f32_16x16x32_bf16 v[10:13], v[202:205], v[182:185], v[228:231]
	v_mfma_f32_16x16x32_bf16 v[26:29], v[236:239], v[186:189], v[10:13]
	v_mfma_f32_16x16x32_bf16 v[10:13], v[202:205], v[190:193], v[232:235]
	v_mfma_f32_16x16x32_bf16 v[30:33], v[236:239], v[194:197], v[10:13]
	v_mfma_f32_16x16x32_bf16 v[10:13], v[240:243], v[182:185], v[142:145]
	v_mfma_f32_16x16x32_bf16 v[14:17], v[240:243], v[190:193], v[146:149]
	v_mfma_f32_16x16x32_bf16 v[10:13], v[138:141], v[186:189], v[10:13]
	v_mfma_f32_16x16x32_bf16 v[14:17], v[138:141], v[194:197], v[14:17]
	s_setprio 0
	s_setprio 3
	v_mfma_f32_16x16x32_bf16 v[34:37], v[18:21], v[2:5], v[150:153]
	v_mfma_f32_16x16x32_bf16 v[18:21], v[18:21], v[244:247], v[154:157]
	v_mfma_f32_16x16x32_bf16 v[54:57], v[22:25], v[248:251], v[18:21]
	v_mfma_f32_16x16x32_bf16 v[18:21], v[38:41], v[2:5], v[158:161]
	v_mfma_f32_16x16x32_bf16 v[50:53], v[22:25], v[6:9], v[34:37]
	v_mfma_f32_16x16x32_bf16 v[34:37], v[198:201], v[6:9], v[18:21]
	v_mfma_f32_16x16x32_bf16 v[18:21], v[38:41], v[244:247], v[162:165]
	v_mfma_f32_16x16x32_bf16 v[38:41], v[198:201], v[248:251], v[18:21]
	v_mfma_f32_16x16x32_bf16 v[18:21], v[202:205], v[2:5], v[166:169]
	v_mfma_f32_16x16x32_bf16 v[2:5], v[240:243], v[2:5], v[174:177]
	v_mfma_f32_16x16x32_bf16 v[18:21], v[236:239], v[6:9], v[18:21]
	v_mfma_f32_16x16x32_bf16 v[22:25], v[202:205], v[244:247], v[170:173]
	v_mfma_f32_16x16x32_bf16 v[2:5], v[138:141], v[6:9], v[2:5]
	v_mfma_f32_16x16x32_bf16 v[6:9], v[240:243], v[244:247], v[178:181]
	v_mfma_f32_16x16x32_bf16 v[22:25], v[236:239], v[248:251], v[22:25]
	v_mfma_f32_16x16x32_bf16 v[6:9], v[138:141], v[248:251], v[6:9]
	s_setprio 0
	s_and_b64 vcc, exec, s[10:11]
	s_barrier
	s_cbranch_vccz .LBB0_367
	s_barrier

.LBB0_403:
	ds_read_b128 v[134:137], v217
	ds_read_b128 v[138:141], v217 offset:1024
	ds_read_b128 v[142:145], v217 offset:2048
	ds_read_b128 v[146:149], v217 offset:3072
	s_add_u32 s62, s28, s30
	s_addc_u32 s63, s29, s31
	s_add_u32 s60, s62, 0x80
	s_addc_u32 s61, s63, 0
	s_add_i32 s59, s42, 0xc000
	ds_read_b128 v[150:153], v216
	ds_read_b128 v[154:157], v216 offset:1024
	ds_read_b128 v[158:161], v216 offset:2048
	ds_read_b128 v[162:165], v216 offset:3072
	ds_read_b128 v[166:169], v216 offset:4096
	ds_read_b128 v[170:173], v216 offset:5120
	ds_read_b128 v[174:177], v216 offset:6144
	ds_read_b128 v[178:181], v216 offset:7168
	ds_read_b128 v[182:185], v217 offset:16384
	ds_read_b128 v[186:189], v217 offset:17408
	ds_read_b128 v[190:193], v217 offset:18432
	ds_read_b128 v[194:197], v217 offset:19456
	s_mov_b32 m0, s59
	s_add_i32 s58, s42, 0xe000
	global_load_lds_dwordx4 v132, s[60:61]
	s_mov_b32 m0, s58
	s_nop 0
	global_load_lds_dwordx4 v130, s[60:61]
	s_waitcnt vmcnt(8)
	s_waitcnt lgkmcnt(0)
	s_barrier
	v_mfma_f32_16x16x32_bf16 v[2:5], v[150:153], v[134:137], v[2:5]
	v_mfma_f32_16x16x32_bf16 v[6:9], v[150:153], v[142:145], v[6:9]
	v_mfma_f32_16x16x32_bf16 v[10:13], v[158:161], v[134:137], v[10:13]
	v_mfma_f32_16x16x32_bf16 v[22:25], v[158:161], v[142:145], v[22:25]
	v_mfma_f32_16x16x32_bf16 v[34:37], v[166:169], v[134:137], v[34:37]
	v_mfma_f32_16x16x32_bf16 v[46:49], v[166:169], v[142:145], v[46:49]
	v_mfma_f32_16x16x32_bf16 v[58:61], v[174:177], v[134:137], v[58:61]
	v_mfma_f32_16x16x32_bf16 v[70:73], v[174:177], v[142:145], v[70:73]
	v_mfma_f32_16x16x32_bf16 v[2:5], v[154:157], v[138:141], v[2:5]
	v_mfma_f32_16x16x32_bf16 v[6:9], v[154:157], v[146:149], v[6:9]
	v_mfma_f32_16x16x32_bf16 v[10:13], v[162:165], v[138:141], v[10:13]
	v_mfma_f32_16x16x32_bf16 v[22:25], v[162:165], v[146:149], v[22:25]
	v_mfma_f32_16x16x32_bf16 v[34:37], v[170:173], v[138:141], v[34:37]
	v_mfma_f32_16x16x32_bf16 v[46:49], v[170:173], v[146:149], v[46:49]
	v_mfma_f32_16x16x32_bf16 v[58:61], v[178:181], v[138:141], v[58:61]
	v_mfma_f32_16x16x32_bf16 v[70:73], v[178:181], v[146:149], v[70:73]
	v_mfma_f32_16x16x32_bf16 v[14:17], v[150:153], v[182:185], v[14:17]
	v_mfma_f32_16x16x32_bf16 v[26:29], v[150:153], v[190:193], v[26:29]
	v_mfma_f32_16x16x32_bf16 v[38:41], v[158:161], v[182:185], v[38:41]
	v_mfma_f32_16x16x32_bf16 v[50:53], v[158:161], v[190:193], v[50:53]
	v_mfma_f32_16x16x32_bf16 v[62:65], v[166:169], v[182:185], v[62:65]
	v_mfma_f32_16x16x32_bf16 v[74:77], v[166:169], v[190:193], v[74:77]
	v_mfma_f32_16x16x32_bf16 v[82:85], v[174:177], v[182:185], v[82:85]
	v_mfma_f32_16x16x32_bf16 v[94:97], v[174:177], v[190:193], v[94:97]
	v_mfma_f32_16x16x32_bf16 v[14:17], v[154:157], v[186:189], v[14:17]
	v_mfma_f32_16x16x32_bf16 v[26:29], v[154:157], v[194:197], v[26:29]
	v_mfma_f32_16x16x32_bf16 v[38:41], v[162:165], v[186:189], v[38:41]
	v_mfma_f32_16x16x32_bf16 v[50:53], v[162:165], v[194:197], v[50:53]
	v_mfma_f32_16x16x32_bf16 v[62:65], v[170:173], v[186:189], v[62:65]
	v_mfma_f32_16x16x32_bf16 v[74:77], v[170:173], v[194:197], v[74:77]
	v_mfma_f32_16x16x32_bf16 v[82:85], v[178:181], v[186:189], v[82:85]
	v_mfma_f32_16x16x32_bf16 v[94:97], v[178:181], v[194:197], v[94:97]
	s_barrier
	ds_read_b128 v[150:153], v216 offset:16384
	ds_read_b128 v[154:157], v216 offset:17408
	ds_read_b128 v[158:161], v216 offset:18432
	ds_read_b128 v[162:165], v216 offset:19456
	ds_read_b128 v[166:169], v216 offset:20480
	ds_read_b128 v[170:173], v216 offset:21504
	ds_read_b128 v[174:177], v216 offset:22528
	ds_read_b128 v[178:181], v216 offset:23552
	s_add_i32 s57, s57, 2
	s_add_u32 s64, s22, s30
	s_addc_u32 s65, s23, s31
	s_add_u32 s60, s64, 0x100
	s_addc_u32 s61, s65, 0
	s_mov_b32 m0, s44
	s_nop 0
	global_load_lds_dwordx4 v132, s[60:61]
	s_mov_b32 m0, s45
	s_nop 0
	global_load_lds_dwordx4 v130, s[60:61]
	s_add_u32 s66, s24, s30
	s_addc_u32 s67, s25, s31
	s_add_u32 s60, s66, 0x100
	s_addc_u32 s61, s67, 0
	s_mov_b32 m0, s42
	s_nop 0
	global_load_lds_dwordx4 v132, s[60:61]
	s_mov_b32 m0, s46
	s_nop 0
	global_load_lds_dwordx4 v130, s[60:61]
	s_add_u32 s68, s26, s30
	s_addc_u32 s69, s27, s31
	s_add_u32 s60, s68, 0x100
	s_addc_u32 s61, s69, 0
	s_mov_b32 m0, s47
	s_nop 0
	global_load_lds_dwordx4 v132, s[60:61]
	s_mov_b32 m0, s48
	s_nop 0
	global_load_lds_dwordx4 v130, s[60:61]
	s_waitcnt vmcnt(8)
	s_waitcnt lgkmcnt(0)
	s_barrier
	v_mfma_f32_16x16x32_bf16 v[18:21], v[150:153], v[134:137], v[18:21]
	v_mfma_f32_16x16x32_bf16 v[30:33], v[150:153], v[142:145], v[30:33]
	v_mfma_f32_16x16x32_bf16 v[42:45], v[158:161], v[134:137], v[42:45]
	v_mfma_f32_16x16x32_bf16 v[54:57], v[158:161], v[142:145], v[54:57]
	v_mfma_f32_16x16x32_bf16 v[66:69], v[166:169], v[134:137], v[66:69]
	v_mfma_f32_16x16x32_bf16 v[78:81], v[166:169], v[142:145], v[78:81]
	v_mfma_f32_16x16x32_bf16 v[86:89], v[174:177], v[134:137], v[86:89]
	v_mfma_f32_16x16x32_bf16 v[98:101], v[174:177], v[142:145], v[98:101]
	v_mfma_f32_16x16x32_bf16 v[18:21], v[154:157], v[138:141], v[18:21]
	v_mfma_f32_16x16x32_bf16 v[30:33], v[154:157], v[146:149], v[30:33]
	v_mfma_f32_16x16x32_bf16 v[42:45], v[162:165], v[138:141], v[42:45]
	v_mfma_f32_16x16x32_bf16 v[54:57], v[162:165], v[146:149], v[54:57]
	v_mfma_f32_16x16x32_bf16 v[66:69], v[170:173], v[138:141], v[66:69]
	v_mfma_f32_16x16x32_bf16 v[78:81], v[170:173], v[146:149], v[78:81]
	v_mfma_f32_16x16x32_bf16 v[86:89], v[178:181], v[138:141], v[86:89]
	v_mfma_f32_16x16x32_bf16 v[98:101], v[178:181], v[146:149], v[98:101]
	v_mfma_f32_16x16x32_bf16 v[90:93], v[150:153], v[182:185], v[90:93]
	v_mfma_f32_16x16x32_bf16 v[102:105], v[150:153], v[190:193], v[102:105]
	v_mfma_f32_16x16x32_bf16 v[106:109], v[158:161], v[182:185], v[106:109]
	v_mfma_f32_16x16x32_bf16 v[110:113], v[158:161], v[190:193], v[110:113]
	v_mfma_f32_16x16x32_bf16 v[114:117], v[166:169], v[182:185], v[114:117]
	v_mfma_f32_16x16x32_bf16 v[118:121], v[166:169], v[190:193], v[118:121]
	v_mfma_f32_16x16x32_bf16 v[122:125], v[174:177], v[182:185], v[122:125]
	v_mfma_f32_16x16x32_bf16 v[126:129], v[174:177], v[190:193], v[126:129]
	v_mfma_f32_16x16x32_bf16 v[90:93], v[154:157], v[186:189], v[90:93]
	v_mfma_f32_16x16x32_bf16 v[102:105], v[154:157], v[194:197], v[102:105]
	v_mfma_f32_16x16x32_bf16 v[106:109], v[162:165], v[186:189], v[106:109]
	v_mfma_f32_16x16x32_bf16 v[110:113], v[162:165], v[194:197], v[110:113]
	v_mfma_f32_16x16x32_bf16 v[114:117], v[170:173], v[186:189], v[114:117]
	v_mfma_f32_16x16x32_bf16 v[118:121], v[170:173], v[194:197], v[118:121]
	v_mfma_f32_16x16x32_bf16 v[122:125], v[178:181], v[186:189], v[122:125]
	v_mfma_f32_16x16x32_bf16 v[126:129], v[178:181], v[194:197], v[126:129]
	s_barrier
	ds_read_b128 v[134:137], v217 offset:32768
	ds_read_b128 v[138:141], v217 offset:33792
	ds_read_b128 v[142:145], v217 offset:34816
	ds_read_b128 v[146:149], v217 offset:35840
	s_add_u32 s60, s62, 0x100
	s_addc_u32 s61, s63, 0
	s_mov_b32 m0, s49
	ds_read_b128 v[150:153], v216 offset:32768
	ds_read_b128 v[154:157], v216 offset:33792
	ds_read_b128 v[158:161], v216 offset:34816
	ds_read_b128 v[162:165], v216 offset:35840
	ds_read_b128 v[166:169], v216 offset:36864
	ds_read_b128 v[170:173], v216 offset:37888
	ds_read_b128 v[174:177], v216 offset:38912
	ds_read_b128 v[178:181], v216 offset:39936
	ds_read_b128 v[182:185], v217 offset:49152
	ds_read_b128 v[186:189], v217 offset:50176
	ds_read_b128 v[190:193], v217 offset:51200
	ds_read_b128 v[194:197], v217 offset:52224
	s_nop 0
	global_load_lds_dwordx4 v132, s[60:61]
	s_mov_b32 m0, s50
	s_nop 0
	global_load_lds_dwordx4 v130, s[60:61]
	s_waitcnt vmcnt(8)
	s_waitcnt lgkmcnt(0)
	s_barrier
	v_mfma_f32_16x16x32_bf16 v[2:5], v[150:153], v[134:137], v[2:5]
	v_mfma_f32_16x16x32_bf16 v[6:9], v[150:153], v[142:145], v[6:9]
	v_mfma_f32_16x16x32_bf16 v[10:13], v[158:161], v[134:137], v[10:13]
	v_mfma_f32_16x16x32_bf16 v[22:25], v[158:161], v[142:145], v[22:25]
	v_mfma_f32_16x16x32_bf16 v[34:37], v[166:169], v[134:137], v[34:37]
	v_mfma_f32_16x16x32_bf16 v[46:49], v[166:169], v[142:145], v[46:49]
	v_mfma_f32_16x16x32_bf16 v[58:61], v[174:177], v[134:137], v[58:61]
	v_mfma_f32_16x16x32_bf16 v[70:73], v[174:177], v[142:145], v[70:73]
	v_mfma_f32_16x16x32_bf16 v[2:5], v[154:157], v[138:141], v[2:5]
	v_mfma_f32_16x16x32_bf16 v[6:9], v[154:157], v[146:149], v[6:9]
	v_mfma_f32_16x16x32_bf16 v[10:13], v[162:165], v[138:141], v[10:13]
	v_mfma_f32_16x16x32_bf16 v[22:25], v[162:165], v[146:149], v[22:25]
	v_mfma_f32_16x16x32_bf16 v[34:37], v[170:173], v[138:141], v[34:37]
	v_mfma_f32_16x16x32_bf16 v[46:49], v[170:173], v[146:149], v[46:49]
	v_mfma_f32_16x16x32_bf16 v[58:61], v[178:181], v[138:141], v[58:61]
	v_mfma_f32_16x16x32_bf16 v[70:73], v[178:181], v[146:149], v[70:73]
	v_mfma_f32_16x16x32_bf16 v[14:17], v[150:153], v[182:185], v[14:17]
	v_mfma_f32_16x16x32_bf16 v[26:29], v[150:153], v[190:193], v[26:29]
	v_mfma_f32_16x16x32_bf16 v[38:41], v[158:161], v[182:185], v[38:41]
	v_mfma_f32_16x16x32_bf16 v[50:53], v[158:161], v[190:193], v[50:53]
	v_mfma_f32_16x16x32_bf16 v[62:65], v[166:169], v[182:185], v[62:65]
	v_mfma_f32_16x16x32_bf16 v[74:77], v[166:169], v[190:193], v[74:77]
	v_mfma_f32_16x16x32_bf16 v[82:85], v[174:177], v[182:185], v[82:85]
	v_mfma_f32_16x16x32_bf16 v[94:97], v[174:177], v[190:193], v[94:97]
	v_mfma_f32_16x16x32_bf16 v[14:17], v[154:157], v[186:189], v[14:17]
	v_mfma_f32_16x16x32_bf16 v[26:29], v[154:157], v[194:197], v[26:29]
	v_mfma_f32_16x16x32_bf16 v[38:41], v[162:165], v[186:189], v[38:41]
	v_mfma_f32_16x16x32_bf16 v[50:53], v[162:165], v[194:197], v[50:53]
	v_mfma_f32_16x16x32_bf16 v[62:65], v[170:173], v[186:189], v[62:65]
	v_mfma_f32_16x16x32_bf16 v[74:77], v[170:173], v[194:197], v[74:77]
	v_mfma_f32_16x16x32_bf16 v[82:85], v[178:181], v[186:189], v[82:85]
	v_mfma_f32_16x16x32_bf16 v[94:97], v[178:181], v[194:197], v[94:97]
	s_barrier
	ds_read_b128 v[150:153], v216 offset:49152
	ds_read_b128 v[154:157], v216 offset:50176
	ds_read_b128 v[158:161], v216 offset:51200
	ds_read_b128 v[162:165], v216 offset:52224
	ds_read_b128 v[166:169], v216 offset:53248
	ds_read_b128 v[170:173], v216 offset:54272
	ds_read_b128 v[174:177], v216 offset:55296
	ds_read_b128 v[178:181], v216 offset:56320
	s_add_u32 s60, s64, 0x180
	s_addc_u32 s61, s65, 0
	s_mov_b32 m0, s51
	s_nop 0
	global_load_lds_dwordx4 v132, s[60:61]
	s_mov_b32 m0, s52
	s_nop 0
	global_load_lds_dwordx4 v130, s[60:61]
	s_add_u32 s60, s66, 0x180
	s_addc_u32 s61, s67, 0
	s_mov_b32 m0, s53
	s_nop 0
	global_load_lds_dwordx4 v132, s[60:61]
	s_mov_b32 m0, s54
	s_nop 0
	global_load_lds_dwordx4 v130, s[60:61]
	s_add_u32 s60, s68, 0x180
	s_addc_u32 s61, s69, 0
	s_mov_b32 m0, s55
	s_nop 0
	global_load_lds_dwordx4 v132, s[60:61]
	s_mov_b32 m0, s56
	s_nop 0
	global_load_lds_dwordx4 v130, s[60:61]
	s_waitcnt vmcnt(8)
	s_waitcnt lgkmcnt(0)
	s_barrier
	v_mfma_f32_16x16x32_bf16 v[18:21], v[150:153], v[134:137], v[18:21]
	v_mfma_f32_16x16x32_bf16 v[30:33], v[150:153], v[142:145], v[30:33]
	v_mfma_f32_16x16x32_bf16 v[42:45], v[158:161], v[134:137], v[42:45]
	v_mfma_f32_16x16x32_bf16 v[54:57], v[158:161], v[142:145], v[54:57]
	v_mfma_f32_16x16x32_bf16 v[66:69], v[166:169], v[134:137], v[66:69]
	v_mfma_f32_16x16x32_bf16 v[78:81], v[166:169], v[142:145], v[78:81]
	v_mfma_f32_16x16x32_bf16 v[86:89], v[174:177], v[134:137], v[86:89]
	v_mfma_f32_16x16x32_bf16 v[98:101], v[174:177], v[142:145], v[98:101]
	v_mfma_f32_16x16x32_bf16 v[18:21], v[154:157], v[138:141], v[18:21]
	v_mfma_f32_16x16x32_bf16 v[30:33], v[154:157], v[146:149], v[30:33]
	v_mfma_f32_16x16x32_bf16 v[42:45], v[162:165], v[138:141], v[42:45]
	v_mfma_f32_16x16x32_bf16 v[54:57], v[162:165], v[146:149], v[54:57]
	v_mfma_f32_16x16x32_bf16 v[66:69], v[170:173], v[138:141], v[66:69]
	v_mfma_f32_16x16x32_bf16 v[78:81], v[170:173], v[146:149], v[78:81]
	v_mfma_f32_16x16x32_bf16 v[86:89], v[178:181], v[138:141], v[86:89]
	v_mfma_f32_16x16x32_bf16 v[98:101], v[178:181], v[146:149], v[98:101]
	v_mfma_f32_16x16x32_bf16 v[90:93], v[150:153], v[182:185], v[90:93]
	v_mfma_f32_16x16x32_bf16 v[102:105], v[150:153], v[190:193], v[102:105]
	v_mfma_f32_16x16x32_bf16 v[106:109], v[158:161], v[182:185], v[106:109]
	v_mfma_f32_16x16x32_bf16 v[110:113], v[158:161], v[190:193], v[110:113]
	v_mfma_f32_16x16x32_bf16 v[114:117], v[166:169], v[182:185], v[114:117]
	v_mfma_f32_16x16x32_bf16 v[118:121], v[166:169], v[190:193], v[118:121]
	v_mfma_f32_16x16x32_bf16 v[122:125], v[174:177], v[182:185], v[122:125]
	v_mfma_f32_16x16x32_bf16 v[126:129], v[174:177], v[190:193], v[126:129]
	v_mfma_f32_16x16x32_bf16 v[90:93], v[154:157], v[186:189], v[90:93]
	v_mfma_f32_16x16x32_bf16 v[102:105], v[154:157], v[194:197], v[102:105]
	v_mfma_f32_16x16x32_bf16 v[106:109], v[162:165], v[186:189], v[106:109]
	v_mfma_f32_16x16x32_bf16 v[110:113], v[162:165], v[194:197], v[110:113]
	v_mfma_f32_16x16x32_bf16 v[114:117], v[170:173], v[186:189], v[114:117]
	v_mfma_f32_16x16x32_bf16 v[118:121], v[170:173], v[194:197], v[118:121]
	v_mfma_f32_16x16x32_bf16 v[122:125], v[178:181], v[186:189], v[122:125]
	v_mfma_f32_16x16x32_bf16 v[126:129], v[178:181], v[194:197], v[126:129]
	s_add_u32 s30, s30, 0x100
	s_addc_u32 s31, s31, 0
	s_cmp_ge_u32 s57, s36
	s_barrier
	s_cbranch_scc0 .LBB0_403
	s_add_u32 s22, s28, s14
	s_addc_u32 s23, s29, s15
	s_mov_b32 m0, s59
	ds_read_b128 v[134:137], v217
	ds_read_b128 v[138:141], v217 offset:1024
	ds_read_b128 v[142:145], v217 offset:2048
	ds_read_b128 v[146:149], v217 offset:3072
	ds_read_b128 v[150:153], v216
	ds_read_b128 v[154:157], v216 offset:1024
	ds_read_b128 v[158:161], v216 offset:2048
	ds_read_b128 v[162:165], v216 offset:3072
	ds_read_b128 v[166:169], v216 offset:4096
	ds_read_b128 v[170:173], v216 offset:5120
	ds_read_b128 v[174:177], v216 offset:6144
	ds_read_b128 v[178:181], v216 offset:7168
	s_nop 0
	global_load_lds_dwordx4 v132, s[22:23]
	s_mov_b32 m0, s58
	s_nop 0
	global_load_lds_dwordx4 v130, s[22:23]
	s_waitcnt vmcnt(8)
	s_barrier
	s_waitcnt lgkmcnt(0)
	s_setprio 3
	s_waitcnt lgkmcnt(0)
	v_mfma_f32_16x16x32_bf16 v[2:5], v[150:153], v[134:137], v[2:5]
	v_mfma_f32_16x16x32_bf16 v[6:9], v[150:153], v[142:145], v[6:9]
	v_mfma_f32_16x16x32_bf16 v[10:13], v[158:161], v[134:137], v[10:13]
	v_mfma_f32_16x16x32_bf16 v[22:25], v[158:161], v[142:145], v[22:25]
	v_mfma_f32_16x16x32_bf16 v[34:37], v[166:169], v[134:137], v[34:37]
	v_mfma_f32_16x16x32_bf16 v[46:49], v[166:169], v[142:145], v[46:49]
	v_mfma_f32_16x16x32_bf16 v[58:61], v[174:177], v[134:137], v[58:61]
	v_mfma_f32_16x16x32_bf16 v[70:73], v[174:177], v[142:145], v[70:73]
	v_mfma_f32_16x16x32_bf16 v[2:5], v[154:157], v[138:141], v[2:5]
	v_mfma_f32_16x16x32_bf16 v[6:9], v[154:157], v[146:149], v[6:9]
	v_mfma_f32_16x16x32_bf16 v[10:13], v[162:165], v[138:141], v[10:13]
	v_mfma_f32_16x16x32_bf16 v[22:25], v[162:165], v[146:149], v[22:25]
	v_mfma_f32_16x16x32_bf16 v[34:37], v[170:173], v[138:141], v[34:37]
	v_mfma_f32_16x16x32_bf16 v[46:49], v[170:173], v[146:149], v[46:49]
	v_mfma_f32_16x16x32_bf16 v[58:61], v[178:181], v[138:141], v[58:61]
	v_mfma_f32_16x16x32_bf16 v[70:73], v[178:181], v[146:149], v[70:73]
	s_setprio 0
	s_barrier
	ds_read_b128 v[182:185], v217 offset:16384
	ds_read_b128 v[186:189], v217 offset:17408
	ds_read_b128 v[190:193], v217 offset:18432
	ds_read_b128 v[194:197], v217 offset:19456
	s_barrier
	s_waitcnt lgkmcnt(0)
	s_setprio 3
	s_waitcnt lgkmcnt(0)
	v_mfma_f32_16x16x32_bf16 v[74:77], v[166:169], v[190:193], v[74:77]
	v_mfma_f32_16x16x32_bf16 v[14:17], v[150:153], v[182:185], v[14:17]
	v_mfma_f32_16x16x32_bf16 v[26:29], v[150:153], v[190:193], v[26:29]
	v_mfma_f32_16x16x32_bf16 v[38:41], v[158:161], v[182:185], v[38:41]
	v_mfma_f32_16x16x32_bf16 v[50:53], v[158:161], v[190:193], v[50:53]
	v_mfma_f32_16x16x32_bf16 v[62:65], v[166:169], v[182:185], v[62:65]
	v_mfma_f32_16x16x32_bf16 v[150:153], v[170:173], v[194:197], v[74:77]
	v_mfma_f32_16x16x32_bf16 v[74:77], v[174:177], v[182:185], v[82:85]
	v_mfma_f32_16x16x32_bf16 v[14:17], v[154:157], v[186:189], v[14:17]
	v_mfma_f32_16x16x32_bf16 v[26:29], v[154:157], v[194:197], v[26:29]
	v_mfma_f32_16x16x32_bf16 v[38:41], v[162:165], v[186:189], v[38:41]
	v_mfma_f32_16x16x32_bf16 v[50:53], v[162:165], v[194:197], v[50:53]
	v_mfma_f32_16x16x32_bf16 v[62:65], v[170:173], v[186:189], v[62:65]
	v_mfma_f32_16x16x32_bf16 v[154:157], v[178:181], v[186:189], v[74:77]
	v_mfma_f32_16x16x32_bf16 v[74:77], v[174:177], v[190:193], v[94:97]
	v_mfma_f32_16x16x32_bf16 v[158:161], v[178:181], v[194:197], v[74:77]
	s_setprio 0
	s_barrier
	s_nop 4
	ds_read_b128 v[74:77], v216 offset:16384
	ds_read_b128 v[82:85], v216 offset:17408
	ds_read_b128 v[94:97], v216 offset:18432
	ds_read_b128 v[162:165], v216 offset:19456
	ds_read_b128 v[166:169], v216 offset:20480
	ds_read_b128 v[170:173], v216 offset:21504
	ds_read_b128 v[174:177], v216 offset:22528
	ds_read_b128 v[178:181], v216 offset:23552
	s_waitcnt vmcnt(4)
	s_barrier
	s_waitcnt lgkmcnt(0)
	s_setprio 3
	s_waitcnt lgkmcnt(0)
	v_mfma_f32_16x16x32_bf16 v[66:69], v[166:169], v[134:137], v[66:69]
	v_mfma_f32_16x16x32_bf16 v[198:201], v[170:173], v[138:141], v[66:69]
	v_mfma_f32_16x16x32_bf16 v[66:69], v[166:169], v[142:145], v[78:81]
	v_mfma_f32_16x16x32_bf16 v[18:21], v[74:77], v[134:137], v[18:21]
	v_mfma_f32_16x16x32_bf16 v[30:33], v[74:77], v[142:145], v[30:33]
	v_mfma_f32_16x16x32_bf16 v[42:45], v[94:97], v[134:137], v[42:45]
	v_mfma_f32_16x16x32_bf16 v[54:57], v[94:97], v[142:145], v[54:57]
	v_mfma_f32_16x16x32_bf16 v[202:205], v[170:173], v[146:149], v[66:69]
	v_mfma_f32_16x16x32_bf16 v[66:69], v[174:177], v[134:137], v[86:89]
	v_mfma_f32_16x16x32_bf16 v[18:21], v[82:85], v[138:141], v[18:21]
	v_mfma_f32_16x16x32_bf16 v[30:33], v[82:85], v[146:149], v[30:33]
	v_mfma_f32_16x16x32_bf16 v[42:45], v[162:165], v[138:141], v[42:45]
	v_mfma_f32_16x16x32_bf16 v[54:57], v[162:165], v[146:149], v[54:57]
	v_mfma_f32_16x16x32_bf16 v[134:137], v[178:181], v[138:141], v[66:69]
	v_mfma_f32_16x16x32_bf16 v[66:69], v[174:177], v[142:145], v[98:101]
	v_mfma_f32_16x16x32_bf16 v[138:141], v[178:181], v[146:149], v[66:69]
	s_setprio 0
	s_setprio 3
	v_mfma_f32_16x16x32_bf16 v[66:69], v[74:77], v[182:185], v[90:93]
	v_mfma_f32_16x16x32_bf16 v[142:145], v[82:85], v[186:189], v[66:69]
	v_mfma_f32_16x16x32_bf16 v[66:69], v[74:77], v[190:193], v[102:105]
	v_mfma_f32_16x16x32_bf16 v[146:149], v[82:85], v[194:197], v[66:69]
	v_mfma_f32_16x16x32_bf16 v[66:69], v[94:97], v[182:185], v[106:109]
	v_mfma_f32_16x16x32_bf16 v[212:215], v[162:165], v[186:189], v[66:69]
	v_mfma_f32_16x16x32_bf16 v[66:69], v[94:97], v[190:193], v[110:113]
	v_mfma_f32_16x16x32_bf16 v[162:165], v[162:165], v[194:197], v[66:69]
	v_mfma_f32_16x16x32_bf16 v[66:69], v[166:169], v[182:185], v[114:117]
	v_mfma_f32_16x16x32_bf16 v[220:223], v[170:173], v[186:189], v[66:69]
	v_mfma_f32_16x16x32_bf16 v[66:69], v[166:169], v[190:193], v[118:121]
	v_mfma_f32_16x16x32_bf16 v[166:169], v[170:173], v[194:197], v[66:69]
	v_mfma_f32_16x16x32_bf16 v[66:69], v[174:177], v[182:185], v[122:125]
	v_mfma_f32_16x16x32_bf16 v[170:173], v[178:181], v[186:189], v[66:69]
	v_mfma_f32_16x16x32_bf16 v[66:69], v[174:177], v[190:193], v[126:129]
	v_mfma_f32_16x16x32_bf16 v[174:177], v[178:181], v[194:197], v[66:69]
	s_setprio 0
	s_barrier
	ds_read_b128 v[178:181], v217 offset:32768
	ds_read_b128 v[182:185], v217 offset:33792
	ds_read_b128 v[186:189], v217 offset:34816
	ds_read_b128 v[190:193], v217 offset:35840
	s_nop 0
	ds_read_b128 v[66:69], v216 offset:32768
	ds_read_b128 v[82:85], v216 offset:33792
	ds_read_b128 v[86:89], v216 offset:34816
	ds_read_b128 v[102:105], v216 offset:35840
	ds_read_b128 v[194:197], v216 offset:36864
	ds_read_b128 v[224:227], v216 offset:37888
	ds_read_b128 v[228:231], v216 offset:38912
	ds_read_b128 v[232:235], v216 offset:39936
	s_waitcnt vmcnt(2)
	s_barrier
	s_waitcnt lgkmcnt(0)
	s_setprio 3
	s_waitcnt lgkmcnt(0)
	v_mfma_f32_16x16x32_bf16 v[2:5], v[66:69], v[178:181], v[2:5]
	v_mfma_f32_16x16x32_bf16 v[122:125], v[82:85], v[182:185], v[2:5]
	v_mfma_f32_16x16x32_bf16 v[2:5], v[66:69], v[186:189], v[6:9]
	v_mfma_f32_16x16x32_bf16 v[126:129], v[82:85], v[190:193], v[2:5]
	v_mfma_f32_16x16x32_bf16 v[2:5], v[86:89], v[178:181], v[10:13]
	v_mfma_f32_16x16x32_bf16 v[106:109], v[102:105], v[182:185], v[2:5]
	v_mfma_f32_16x16x32_bf16 v[2:5], v[86:89], v[186:189], v[22:25]
	v_mfma_f32_16x16x32_bf16 v[110:113], v[102:105], v[190:193], v[2:5]
	v_mfma_f32_16x16x32_bf16 v[2:5], v[194:197], v[178:181], v[34:37]
	v_mfma_f32_16x16x32_bf16 v[90:93], v[224:227], v[182:185], v[2:5]
	v_mfma_f32_16x16x32_bf16 v[2:5], v[194:197], v[186:189], v[46:49]
	v_mfma_f32_16x16x32_bf16 v[94:97], v[224:227], v[190:193], v[2:5]
	v_mfma_f32_16x16x32_bf16 v[2:5], v[228:231], v[178:181], v[58:61]
	v_mfma_f32_16x16x32_bf16 v[74:77], v[232:235], v[182:185], v[2:5]
	v_mfma_f32_16x16x32_bf16 v[2:5], v[228:231], v[186:189], v[70:73]
	v_mfma_f32_16x16x32_bf16 v[78:81], v[232:235], v[190:193], v[2:5]
	s_setprio 0
	s_barrier
	s_nop 4
	ds_read_b128 v[2:5], v217 offset:49152
	ds_read_b128 v[6:9], v217 offset:50176
	ds_read_b128 v[236:239], v217 offset:51200
	ds_read_b128 v[240:243], v217 offset:52224
	s_waitcnt vmcnt(0)
	s_barrier
	s_waitcnt lgkmcnt(0)
	s_setprio 3
	s_waitcnt lgkmcnt(0)
	v_mfma_f32_16x16x32_bf16 v[10:13], v[66:69], v[2:5], v[14:17]
	v_mfma_f32_16x16x32_bf16 v[114:117], v[82:85], v[6:9], v[10:13]
	v_mfma_f32_16x16x32_bf16 v[10:13], v[66:69], v[236:239], v[26:29]
	v_mfma_f32_16x16x32_bf16 v[118:121], v[82:85], v[240:243], v[10:13]
	v_mfma_f32_16x16x32_bf16 v[10:13], v[86:89], v[2:5], v[38:41]
	v_mfma_f32_16x16x32_bf16 v[98:101], v[102:105], v[6:9], v[10:13]
	v_mfma_f32_16x16x32_bf16 v[10:13], v[86:89], v[236:239], v[50:53]
	v_mfma_f32_16x16x32_bf16 v[102:105], v[102:105], v[240:243], v[10:13]
	v_mfma_f32_16x16x32_bf16 v[10:13], v[194:197], v[2:5], v[62:65]
	v_mfma_f32_16x16x32_bf16 v[82:85], v[224:227], v[6:9], v[10:13]
	v_mfma_f32_16x16x32_bf16 v[10:13], v[194:197], v[236:239], v[150:153]
	v_mfma_f32_16x16x32_bf16 v[86:89], v[224:227], v[240:243], v[10:13]
	v_mfma_f32_16x16x32_bf16 v[10:13], v[228:231], v[2:5], v[154:157]
	v_mfma_f32_16x16x32_bf16 v[66:69], v[232:235], v[6:9], v[10:13]
	v_mfma_f32_16x16x32_bf16 v[10:13], v[228:231], v[236:239], v[158:161]
	v_mfma_f32_16x16x32_bf16 v[70:73], v[232:235], v[240:243], v[10:13]
	s_setprio 0
	s_barrier
	ds_read_b128 v[22:25], v216 offset:49152
	ds_read_b128 v[34:37], v216 offset:50176
	ds_read_b128 v[38:41], v216 offset:51200
	ds_read_b128 v[150:153], v216 offset:52224
	ds_read_b128 v[154:157], v216 offset:53248
	ds_read_b128 v[158:161], v216 offset:54272
	ds_read_b128 v[194:197], v216 offset:55296
	ds_read_b128 v[224:227], v216 offset:56320
	s_barrier
	s_waitcnt lgkmcnt(0)
	s_setprio 3
	s_waitcnt lgkmcnt(0)
	v_mfma_f32_16x16x32_bf16 v[10:13], v[22:25], v[178:181], v[18:21]
	v_mfma_f32_16x16x32_bf16 v[58:61], v[34:37], v[182:185], v[10:13]
	v_mfma_f32_16x16x32_bf16 v[10:13], v[22:25], v[186:189], v[30:33]
	v_mfma_f32_16x16x32_bf16 v[62:65], v[34:37], v[190:193], v[10:13]
	v_mfma_f32_16x16x32_bf16 v[10:13], v[38:41], v[178:181], v[42:45]
	v_mfma_f32_16x16x32_bf16 v[42:45], v[150:153], v[182:185], v[10:13]
	v_mfma_f32_16x16x32_bf16 v[10:13], v[38:41], v[186:189], v[54:57]
	v_mfma_f32_16x16x32_bf16 v[46:49], v[150:153], v[190:193], v[10:13]
	v_mfma_f32_16x16x32_bf16 v[10:13], v[154:157], v[178:181], v[198:201]
	v_mfma_f32_16x16x32_bf16 v[26:29], v[158:161], v[182:185], v[10:13]
	v_mfma_f32_16x16x32_bf16 v[10:13], v[154:157], v[186:189], v[202:205]
	v_mfma_f32_16x16x32_bf16 v[30:33], v[158:161], v[190:193], v[10:13]
	v_mfma_f32_16x16x32_bf16 v[10:13], v[194:197], v[178:181], v[134:137]
	v_mfma_f32_16x16x32_bf16 v[14:17], v[194:197], v[186:189], v[138:141]
	v_mfma_f32_16x16x32_bf16 v[10:13], v[224:227], v[182:185], v[10:13]
	v_mfma_f32_16x16x32_bf16 v[14:17], v[224:227], v[190:193], v[14:17]
	s_setprio 0
	s_setprio 3
	v_mfma_f32_16x16x32_bf16 v[18:21], v[22:25], v[2:5], v[142:145]
	v_mfma_f32_16x16x32_bf16 v[50:53], v[34:37], v[6:9], v[18:21]
	v_mfma_f32_16x16x32_bf16 v[18:21], v[22:25], v[236:239], v[146:149]
	v_mfma_f32_16x16x32_bf16 v[54:57], v[34:37], v[240:243], v[18:21]
	v_mfma_f32_16x16x32_bf16 v[18:21], v[38:41], v[2:5], v[212:215]
	v_mfma_f32_16x16x32_bf16 v[34:37], v[150:153], v[6:9], v[18:21]
	v_mfma_f32_16x16x32_bf16 v[18:21], v[38:41], v[236:239], v[162:165]
	v_mfma_f32_16x16x32_bf16 v[38:41], v[150:153], v[240:243], v[18:21]
	v_mfma_f32_16x16x32_bf16 v[18:21], v[154:157], v[2:5], v[220:223]
	v_mfma_f32_16x16x32_bf16 v[2:5], v[194:197], v[2:5], v[170:173]
	v_mfma_f32_16x16x32_bf16 v[18:21], v[158:161], v[6:9], v[18:21]
	v_mfma_f32_16x16x32_bf16 v[22:25], v[154:157], v[236:239], v[166:169]
	v_mfma_f32_16x16x32_bf16 v[2:5], v[224:227], v[6:9], v[2:5]
	v_mfma_f32_16x16x32_bf16 v[6:9], v[194:197], v[236:239], v[174:177]
	v_mfma_f32_16x16x32_bf16 v[22:25], v[158:161], v[240:243], v[22:25]
	v_mfma_f32_16x16x32_bf16 v[6:9], v[224:227], v[240:243], v[6:9]
	s_setprio 0
	s_and_b64 vcc, exec, s[16:17]
	s_barrier
	s_cbranch_vccz .LBB0_406
	s_barrier

.LBB0_468:
	ds_read_b128 v[138:141], v137
	ds_read_b128 v[142:145], v137 offset:1024
	ds_read_b128 v[146:149], v137 offset:2048
	ds_read_b128 v[150:153], v137 offset:3072
	s_add_u32 s57, s18, s16
	s_addc_u32 s60, s19, s17
	s_add_u32 s58, s57, 0x180
	s_addc_u32 s59, s60, 0
	s_mov_b32 m0, s40
	ds_read_b128 v[154:157], v136
	ds_read_b128 v[158:161], v136 offset:1024
	ds_read_b128 v[162:165], v136 offset:2048
	ds_read_b128 v[166:169], v136 offset:3072
	ds_read_b128 v[170:173], v136 offset:4096
	ds_read_b128 v[174:177], v136 offset:5120
	ds_read_b128 v[178:181], v136 offset:6144
	ds_read_b128 v[182:185], v136 offset:7168
	ds_read_b128 v[186:189], v137 offset:16384
	ds_read_b128 v[190:193], v137 offset:17408
	ds_read_b128 v[194:197], v137 offset:18432
	ds_read_b128 v[198:201], v137 offset:19456
	s_nop 0
	global_load_lds_dwordx4 v130, s[58:59]
	s_mov_b32 m0, s41
	s_nop 0
	global_load_lds_dwordx4 v132, s[58:59]
	s_waitcnt vmcnt(8)
	s_waitcnt lgkmcnt(0)
	s_barrier
	v_mfma_f32_16x16x32_bf16 v[30:33], v[154:157], v[138:141], v[30:33]
	v_mfma_f32_16x16x32_bf16 v[26:29], v[154:157], v[146:149], v[26:29]
	v_mfma_f32_16x16x32_bf16 v[22:25], v[162:165], v[138:141], v[22:25]
	v_mfma_f32_16x16x32_bf16 v[18:21], v[162:165], v[146:149], v[18:21]
	v_mfma_f32_16x16x32_bf16 v[14:17], v[170:173], v[138:141], v[14:17]
	v_mfma_f32_16x16x32_bf16 v[10:13], v[170:173], v[146:149], v[10:13]
	v_mfma_f32_16x16x32_bf16 v[6:9], v[178:181], v[138:141], v[6:9]
	v_mfma_f32_16x16x32_bf16 v[2:5], v[178:181], v[146:149], v[2:5]
	v_mfma_f32_16x16x32_bf16 v[30:33], v[158:161], v[142:145], v[30:33]
	v_mfma_f32_16x16x32_bf16 v[26:29], v[158:161], v[150:153], v[26:29]
	v_mfma_f32_16x16x32_bf16 v[22:25], v[166:169], v[142:145], v[22:25]
	v_mfma_f32_16x16x32_bf16 v[18:21], v[166:169], v[150:153], v[18:21]
	v_mfma_f32_16x16x32_bf16 v[14:17], v[174:177], v[142:145], v[14:17]
	v_mfma_f32_16x16x32_bf16 v[10:13], v[174:177], v[150:153], v[10:13]
	v_mfma_f32_16x16x32_bf16 v[6:9], v[182:185], v[142:145], v[6:9]
	v_mfma_f32_16x16x32_bf16 v[2:5], v[182:185], v[150:153], v[2:5]
	v_mfma_f32_16x16x32_bf16 v[62:65], v[154:157], v[186:189], v[62:65]
	v_mfma_f32_16x16x32_bf16 v[58:61], v[154:157], v[194:197], v[58:61]
	v_mfma_f32_16x16x32_bf16 v[54:57], v[162:165], v[186:189], v[54:57]
	v_mfma_f32_16x16x32_bf16 v[50:53], v[162:165], v[194:197], v[50:53]
	v_mfma_f32_16x16x32_bf16 v[46:49], v[170:173], v[186:189], v[46:49]
	v_mfma_f32_16x16x32_bf16 v[42:45], v[170:173], v[194:197], v[42:45]
	v_mfma_f32_16x16x32_bf16 v[38:41], v[178:181], v[186:189], v[38:41]
	v_mfma_f32_16x16x32_bf16 v[34:37], v[178:181], v[194:197], v[34:37]
	v_mfma_f32_16x16x32_bf16 v[62:65], v[158:161], v[190:193], v[62:65]
	v_mfma_f32_16x16x32_bf16 v[58:61], v[158:161], v[198:201], v[58:61]
	v_mfma_f32_16x16x32_bf16 v[54:57], v[166:169], v[190:193], v[54:57]
	v_mfma_f32_16x16x32_bf16 v[50:53], v[166:169], v[198:201], v[50:53]
	v_mfma_f32_16x16x32_bf16 v[46:49], v[174:177], v[190:193], v[46:49]
	v_mfma_f32_16x16x32_bf16 v[42:45], v[174:177], v[198:201], v[42:45]
	v_mfma_f32_16x16x32_bf16 v[38:41], v[182:185], v[190:193], v[38:41]
	v_mfma_f32_16x16x32_bf16 v[34:37], v[182:185], v[198:201], v[34:37]
	s_barrier
	ds_read_b128 v[154:157], v136 offset:16384
	ds_read_b128 v[158:161], v136 offset:17408
	ds_read_b128 v[162:165], v136 offset:18432
	ds_read_b128 v[166:169], v136 offset:19456
	ds_read_b128 v[170:173], v136 offset:20480
	ds_read_b128 v[174:177], v136 offset:21504
	ds_read_b128 v[178:181], v136 offset:22528
	ds_read_b128 v[182:185], v136 offset:23552
	s_add_u32 s61, s51, s16
	s_addc_u32 s62, s52, s17
	s_add_u32 s58, s61, 0x200
	s_addc_u32 s59, s62, 0
	s_mov_b32 m0, s26
	s_nop 0
	global_load_lds_dwordx4 v130, s[58:59]
	s_mov_b32 m0, s27
	s_nop 0
	global_load_lds_dwordx4 v132, s[58:59]
	s_add_u32 s63, s13, s16
	s_addc_u32 s64, s53, s17
	s_add_u32 s58, s63, 0x200
	s_addc_u32 s59, s64, 0
	s_mov_b32 m0, s25
	s_nop 0
	global_load_lds_dwordx4 v130, s[58:59]
	s_mov_b32 m0, s28
	s_nop 0
	global_load_lds_dwordx4 v132, s[58:59]
	s_add_u32 s65, s54, s16
	s_addc_u32 s66, s55, s17
	s_add_u32 s58, s65, 0x200
	s_addc_u32 s59, s66, 0
	s_mov_b32 m0, s29
	s_nop 0
	global_load_lds_dwordx4 v130, s[58:59]
	s_mov_b32 m0, s30
	s_nop 0
	global_load_lds_dwordx4 v132, s[58:59]
	s_waitcnt vmcnt(8)
	s_waitcnt lgkmcnt(0)
	s_barrier
	v_mfma_f32_16x16x32_bf16 v[94:97], v[154:157], v[138:141], v[94:97]
	v_mfma_f32_16x16x32_bf16 v[90:93], v[154:157], v[146:149], v[90:93]
	v_mfma_f32_16x16x32_bf16 v[86:89], v[162:165], v[138:141], v[86:89]
	v_mfma_f32_16x16x32_bf16 v[82:85], v[162:165], v[146:149], v[82:85]
	v_mfma_f32_16x16x32_bf16 v[78:81], v[170:173], v[138:141], v[78:81]
	v_mfma_f32_16x16x32_bf16 v[74:77], v[170:173], v[146:149], v[74:77]
	v_mfma_f32_16x16x32_bf16 v[70:73], v[178:181], v[138:141], v[70:73]
	v_mfma_f32_16x16x32_bf16 v[66:69], v[178:181], v[146:149], v[66:69]
	v_mfma_f32_16x16x32_bf16 v[94:97], v[158:161], v[142:145], v[94:97]
	v_mfma_f32_16x16x32_bf16 v[90:93], v[158:161], v[150:153], v[90:93]
	v_mfma_f32_16x16x32_bf16 v[86:89], v[166:169], v[142:145], v[86:89]
	v_mfma_f32_16x16x32_bf16 v[82:85], v[166:169], v[150:153], v[82:85]
	v_mfma_f32_16x16x32_bf16 v[78:81], v[174:177], v[142:145], v[78:81]
	v_mfma_f32_16x16x32_bf16 v[74:77], v[174:177], v[150:153], v[74:77]
	v_mfma_f32_16x16x32_bf16 v[70:73], v[182:185], v[142:145], v[70:73]
	v_mfma_f32_16x16x32_bf16 v[66:69], v[182:185], v[150:153], v[66:69]
	v_mfma_f32_16x16x32_bf16 v[126:129], v[154:157], v[186:189], v[126:129]
	v_mfma_f32_16x16x32_bf16 v[122:125], v[154:157], v[194:197], v[122:125]
	v_mfma_f32_16x16x32_bf16 v[118:121], v[162:165], v[186:189], v[118:121]
	v_mfma_f32_16x16x32_bf16 v[114:117], v[162:165], v[194:197], v[114:117]
	v_mfma_f32_16x16x32_bf16 v[110:113], v[170:173], v[186:189], v[110:113]
	v_mfma_f32_16x16x32_bf16 v[106:109], v[170:173], v[194:197], v[106:109]
	v_mfma_f32_16x16x32_bf16 v[102:105], v[178:181], v[186:189], v[102:105]
	v_mfma_f32_16x16x32_bf16 v[98:101], v[178:181], v[194:197], v[98:101]
	v_mfma_f32_16x16x32_bf16 v[126:129], v[158:161], v[190:193], v[126:129]
	v_mfma_f32_16x16x32_bf16 v[122:125], v[158:161], v[198:201], v[122:125]
	v_mfma_f32_16x16x32_bf16 v[118:121], v[166:169], v[190:193], v[118:121]
	v_mfma_f32_16x16x32_bf16 v[114:117], v[166:169], v[198:201], v[114:117]
	v_mfma_f32_16x16x32_bf16 v[110:113], v[174:177], v[190:193], v[110:113]
	v_mfma_f32_16x16x32_bf16 v[106:109], v[174:177], v[198:201], v[106:109]
	v_mfma_f32_16x16x32_bf16 v[102:105], v[182:185], v[190:193], v[102:105]
	v_mfma_f32_16x16x32_bf16 v[98:101], v[182:185], v[198:201], v[98:101]
	s_barrier
	ds_read_b128 v[138:141], v137 offset:32768
	ds_read_b128 v[142:145], v137 offset:33792
	ds_read_b128 v[146:149], v137 offset:34816
	ds_read_b128 v[150:153], v137 offset:35840
	s_add_u32 s58, s57, 0x200
	s_addc_u32 s59, s60, 0
	s_mov_b32 m0, s31
	ds_read_b128 v[154:157], v136 offset:32768
	ds_read_b128 v[158:161], v136 offset:33792
	ds_read_b128 v[162:165], v136 offset:34816
	ds_read_b128 v[166:169], v136 offset:35840
	ds_read_b128 v[170:173], v136 offset:36864
	ds_read_b128 v[174:177], v136 offset:37888
	ds_read_b128 v[178:181], v136 offset:38912
	ds_read_b128 v[182:185], v136 offset:39936
	ds_read_b128 v[186:189], v137 offset:49152
	ds_read_b128 v[190:193], v137 offset:50176
	ds_read_b128 v[194:197], v137 offset:51200
	ds_read_b128 v[198:201], v137 offset:52224
	s_nop 0
	global_load_lds_dwordx4 v130, s[58:59]
	s_mov_b32 m0, s33
	s_nop 0
	global_load_lds_dwordx4 v132, s[58:59]
	s_waitcnt vmcnt(8)
	s_waitcnt lgkmcnt(0)
	s_barrier
	v_mfma_f32_16x16x32_bf16 v[30:33], v[154:157], v[138:141], v[30:33]
	v_mfma_f32_16x16x32_bf16 v[26:29], v[154:157], v[146:149], v[26:29]
	v_mfma_f32_16x16x32_bf16 v[22:25], v[162:165], v[138:141], v[22:25]
	v_mfma_f32_16x16x32_bf16 v[18:21], v[162:165], v[146:149], v[18:21]
	v_mfma_f32_16x16x32_bf16 v[14:17], v[170:173], v[138:141], v[14:17]
	v_mfma_f32_16x16x32_bf16 v[10:13], v[170:173], v[146:149], v[10:13]
	v_mfma_f32_16x16x32_bf16 v[6:9], v[178:181], v[138:141], v[6:9]
	v_mfma_f32_16x16x32_bf16 v[2:5], v[178:181], v[146:149], v[2:5]
	v_mfma_f32_16x16x32_bf16 v[30:33], v[158:161], v[142:145], v[30:33]
	v_mfma_f32_16x16x32_bf16 v[26:29], v[158:161], v[150:153], v[26:29]
	v_mfma_f32_16x16x32_bf16 v[22:25], v[166:169], v[142:145], v[22:25]
	v_mfma_f32_16x16x32_bf16 v[18:21], v[166:169], v[150:153], v[18:21]
	v_mfma_f32_16x16x32_bf16 v[14:17], v[174:177], v[142:145], v[14:17]
	v_mfma_f32_16x16x32_bf16 v[10:13], v[174:177], v[150:153], v[10:13]
	v_mfma_f32_16x16x32_bf16 v[6:9], v[182:185], v[142:145], v[6:9]
	v_mfma_f32_16x16x32_bf16 v[2:5], v[182:185], v[150:153], v[2:5]
	v_mfma_f32_16x16x32_bf16 v[62:65], v[154:157], v[186:189], v[62:65]
	v_mfma_f32_16x16x32_bf16 v[58:61], v[154:157], v[194:197], v[58:61]
	v_mfma_f32_16x16x32_bf16 v[54:57], v[162:165], v[186:189], v[54:57]
	v_mfma_f32_16x16x32_bf16 v[50:53], v[162:165], v[194:197], v[50:53]
	v_mfma_f32_16x16x32_bf16 v[46:49], v[170:173], v[186:189], v[46:49]
	v_mfma_f32_16x16x32_bf16 v[42:45], v[170:173], v[194:197], v[42:45]
	v_mfma_f32_16x16x32_bf16 v[38:41], v[178:181], v[186:189], v[38:41]
	v_mfma_f32_16x16x32_bf16 v[34:37], v[178:181], v[194:197], v[34:37]
	v_mfma_f32_16x16x32_bf16 v[62:65], v[158:161], v[190:193], v[62:65]
	v_mfma_f32_16x16x32_bf16 v[58:61], v[158:161], v[198:201], v[58:61]
	v_mfma_f32_16x16x32_bf16 v[54:57], v[166:169], v[190:193], v[54:57]
	v_mfma_f32_16x16x32_bf16 v[50:53], v[166:169], v[198:201], v[50:53]
	v_mfma_f32_16x16x32_bf16 v[46:49], v[174:177], v[190:193], v[46:49]
	v_mfma_f32_16x16x32_bf16 v[42:45], v[174:177], v[198:201], v[42:45]
	v_mfma_f32_16x16x32_bf16 v[38:41], v[182:185], v[190:193], v[38:41]
	v_mfma_f32_16x16x32_bf16 v[34:37], v[182:185], v[198:201], v[34:37]
	s_barrier
	ds_read_b128 v[154:157], v136 offset:49152
	ds_read_b128 v[158:161], v136 offset:50176
	ds_read_b128 v[162:165], v136 offset:51200
	ds_read_b128 v[166:169], v136 offset:52224
	ds_read_b128 v[170:173], v136 offset:53248
	ds_read_b128 v[174:177], v136 offset:54272
	ds_read_b128 v[178:181], v136 offset:55296
	ds_read_b128 v[182:185], v136 offset:56320
	s_add_u32 s58, s61, 0x280
	s_addc_u32 s59, s62, 0
	s_mov_b32 m0, s34
	s_nop 0
	global_load_lds_dwordx4 v130, s[58:59]
	s_mov_b32 m0, s35
	s_nop 0
	global_load_lds_dwordx4 v132, s[58:59]
	s_add_u32 s58, s63, 0x280
	s_addc_u32 s59, s64, 0
	s_mov_b32 m0, s36
	s_nop 0
	global_load_lds_dwordx4 v130, s[58:59]
	s_mov_b32 m0, s37
	s_nop 0
	global_load_lds_dwordx4 v132, s[58:59]
	s_add_u32 s58, s65, 0x280
	s_addc_u32 s59, s66, 0
	s_mov_b32 m0, s38
	s_nop 0
	global_load_lds_dwordx4 v130, s[58:59]
	s_mov_b32 m0, s39
	s_nop 0
	global_load_lds_dwordx4 v132, s[58:59]
	s_waitcnt vmcnt(8)
	s_waitcnt lgkmcnt(0)
	s_barrier
	v_mfma_f32_16x16x32_bf16 v[94:97], v[154:157], v[138:141], v[94:97]
	v_mfma_f32_16x16x32_bf16 v[90:93], v[154:157], v[146:149], v[90:93]
	v_mfma_f32_16x16x32_bf16 v[86:89], v[162:165], v[138:141], v[86:89]
	v_mfma_f32_16x16x32_bf16 v[82:85], v[162:165], v[146:149], v[82:85]
	v_mfma_f32_16x16x32_bf16 v[78:81], v[170:173], v[138:141], v[78:81]
	v_mfma_f32_16x16x32_bf16 v[74:77], v[170:173], v[146:149], v[74:77]
	v_mfma_f32_16x16x32_bf16 v[70:73], v[178:181], v[138:141], v[70:73]
	v_mfma_f32_16x16x32_bf16 v[66:69], v[178:181], v[146:149], v[66:69]
	v_mfma_f32_16x16x32_bf16 v[94:97], v[158:161], v[142:145], v[94:97]
	v_mfma_f32_16x16x32_bf16 v[90:93], v[158:161], v[150:153], v[90:93]
	v_mfma_f32_16x16x32_bf16 v[86:89], v[166:169], v[142:145], v[86:89]
	v_mfma_f32_16x16x32_bf16 v[82:85], v[166:169], v[150:153], v[82:85]
	v_mfma_f32_16x16x32_bf16 v[78:81], v[174:177], v[142:145], v[78:81]
	v_mfma_f32_16x16x32_bf16 v[74:77], v[174:177], v[150:153], v[74:77]
	v_mfma_f32_16x16x32_bf16 v[70:73], v[182:185], v[142:145], v[70:73]
	v_mfma_f32_16x16x32_bf16 v[66:69], v[182:185], v[150:153], v[66:69]
	v_mfma_f32_16x16x32_bf16 v[126:129], v[154:157], v[186:189], v[126:129]
	v_mfma_f32_16x16x32_bf16 v[122:125], v[154:157], v[194:197], v[122:125]
	v_mfma_f32_16x16x32_bf16 v[118:121], v[162:165], v[186:189], v[118:121]
	v_mfma_f32_16x16x32_bf16 v[114:117], v[162:165], v[194:197], v[114:117]
	v_mfma_f32_16x16x32_bf16 v[110:113], v[170:173], v[186:189], v[110:113]
	v_mfma_f32_16x16x32_bf16 v[106:109], v[170:173], v[194:197], v[106:109]
	v_mfma_f32_16x16x32_bf16 v[102:105], v[178:181], v[186:189], v[102:105]
	v_mfma_f32_16x16x32_bf16 v[98:101], v[178:181], v[194:197], v[98:101]
	v_mfma_f32_16x16x32_bf16 v[126:129], v[158:161], v[190:193], v[126:129]
	v_mfma_f32_16x16x32_bf16 v[122:125], v[158:161], v[198:201], v[122:125]
	v_mfma_f32_16x16x32_bf16 v[118:121], v[166:169], v[190:193], v[118:121]
	v_mfma_f32_16x16x32_bf16 v[114:117], v[166:169], v[198:201], v[114:117]
	v_mfma_f32_16x16x32_bf16 v[110:113], v[174:177], v[190:193], v[110:113]
	v_mfma_f32_16x16x32_bf16 v[106:109], v[174:177], v[198:201], v[106:109]
	v_mfma_f32_16x16x32_bf16 v[102:105], v[182:185], v[190:193], v[102:105]
	v_mfma_f32_16x16x32_bf16 v[98:101], v[182:185], v[198:201], v[98:101]
	s_add_i32 s56, s56, 2
	s_add_u32 s16, s16, 0x100
	s_addc_u32 s17, s17, 0
	s_cmp_gt_u32 s56, 11
	s_barrier
	s_cbranch_scc0 .LBB0_468
	s_lshl_b64 s[14:15], s[14:15], 1
	s_add_u32 s14, s42, s14
	s_addc_u32 s15, s43, s15
	s_mov_b32 m0, s40
	ds_read_b128 v[142:145], v137
	ds_read_b128 v[146:149], v137 offset:1024
	ds_read_b128 v[150:153], v137 offset:2048
	ds_read_b128 v[154:157], v137 offset:3072
	ds_read_b128 v[158:161], v136
	ds_read_b128 v[162:165], v136 offset:1024
	ds_read_b128 v[166:169], v136 offset:2048
	ds_read_b128 v[170:173], v136 offset:3072
	ds_read_b128 v[174:177], v136 offset:4096
	ds_read_b128 v[178:181], v136 offset:5120
	ds_read_b128 v[182:185], v136 offset:6144
	ds_read_b128 v[186:189], v136 offset:7168
	s_nop 0
	global_load_lds_dwordx4 v130, s[14:15]
	s_mov_b32 m0, s41
	s_nop 0
	global_load_lds_dwordx4 v132, s[14:15]
	s_waitcnt vmcnt(8)
	s_barrier
	s_waitcnt lgkmcnt(0)
	s_setprio 3
	s_waitcnt lgkmcnt(0)
	v_mfma_f32_16x16x32_bf16 v[30:33], v[158:161], v[142:145], v[30:33]
	v_mfma_f32_16x16x32_bf16 v[26:29], v[158:161], v[150:153], v[26:29]
	v_mfma_f32_16x16x32_bf16 v[22:25], v[166:169], v[142:145], v[22:25]
	v_mfma_f32_16x16x32_bf16 v[18:21], v[166:169], v[150:153], v[18:21]
	v_mfma_f32_16x16x32_bf16 v[14:17], v[174:177], v[142:145], v[14:17]
	v_mfma_f32_16x16x32_bf16 v[10:13], v[174:177], v[150:153], v[10:13]
	v_mfma_f32_16x16x32_bf16 v[6:9], v[182:185], v[142:145], v[6:9]
	v_mfma_f32_16x16x32_bf16 v[2:5], v[182:185], v[150:153], v[2:5]
	v_mfma_f32_16x16x32_bf16 v[30:33], v[162:165], v[146:149], v[30:33]
	v_mfma_f32_16x16x32_bf16 v[26:29], v[162:165], v[154:157], v[26:29]
	v_mfma_f32_16x16x32_bf16 v[22:25], v[170:173], v[146:149], v[22:25]
	v_mfma_f32_16x16x32_bf16 v[18:21], v[170:173], v[154:157], v[18:21]
	v_mfma_f32_16x16x32_bf16 v[14:17], v[178:181], v[146:149], v[14:17]
	v_mfma_f32_16x16x32_bf16 v[10:13], v[178:181], v[154:157], v[10:13]
	v_mfma_f32_16x16x32_bf16 v[6:9], v[186:189], v[146:149], v[6:9]
	v_mfma_f32_16x16x32_bf16 v[2:5], v[186:189], v[154:157], v[2:5]
	s_setprio 0
	s_barrier
	ds_read_b128 v[190:193], v137 offset:16384
	ds_read_b128 v[194:197], v137 offset:17408
	ds_read_b128 v[198:201], v137 offset:18432
	ds_read_b128 v[202:205], v137 offset:19456
	s_barrier
	s_waitcnt lgkmcnt(0)
	s_setprio 3
	s_waitcnt lgkmcnt(0)
	v_mfma_f32_16x16x32_bf16 v[62:65], v[158:161], v[190:193], v[62:65]
	v_mfma_f32_16x16x32_bf16 v[58:61], v[158:161], v[198:201], v[58:61]
	v_mfma_f32_16x16x32_bf16 v[54:57], v[166:169], v[190:193], v[54:57]
	v_mfma_f32_16x16x32_bf16 v[50:53], v[166:169], v[198:201], v[50:53]
	v_mfma_f32_16x16x32_bf16 v[46:49], v[174:177], v[190:193], v[46:49]
	v_mfma_f32_16x16x32_bf16 v[42:45], v[174:177], v[198:201], v[42:45]
	v_mfma_f32_16x16x32_bf16 v[38:41], v[182:185], v[190:193], v[38:41]
	v_mfma_f32_16x16x32_bf16 v[34:37], v[182:185], v[198:201], v[34:37]
	v_mfma_f32_16x16x32_bf16 v[62:65], v[162:165], v[194:197], v[62:65]
	v_mfma_f32_16x16x32_bf16 v[58:61], v[162:165], v[202:205], v[58:61]
	v_mfma_f32_16x16x32_bf16 v[54:57], v[170:173], v[194:197], v[54:57]
	v_mfma_f32_16x16x32_bf16 v[50:53], v[170:173], v[202:205], v[50:53]
	v_mfma_f32_16x16x32_bf16 v[46:49], v[178:181], v[194:197], v[46:49]
	v_mfma_f32_16x16x32_bf16 v[42:45], v[178:181], v[202:205], v[42:45]
	v_mfma_f32_16x16x32_bf16 v[38:41], v[186:189], v[194:197], v[38:41]
	v_mfma_f32_16x16x32_bf16 v[34:37], v[186:189], v[202:205], v[34:37]
	s_setprio 0
	s_barrier
	ds_read_b128 v[158:161], v136 offset:16384
	ds_read_b128 v[162:165], v136 offset:17408
	ds_read_b128 v[166:169], v136 offset:18432
	ds_read_b128 v[170:173], v136 offset:19456
	ds_read_b128 v[174:177], v136 offset:20480
	ds_read_b128 v[178:181], v136 offset:21504
	ds_read_b128 v[182:185], v136 offset:22528
	ds_read_b128 v[186:189], v136 offset:23552
	s_waitcnt vmcnt(4)
	s_barrier
	s_waitcnt lgkmcnt(0)
	s_setprio 3
	s_waitcnt lgkmcnt(0)
	v_mfma_f32_16x16x32_bf16 v[94:97], v[158:161], v[142:145], v[94:97]
	v_mfma_f32_16x16x32_bf16 v[90:93], v[158:161], v[150:153], v[90:93]
	v_mfma_f32_16x16x32_bf16 v[86:89], v[166:169], v[142:145], v[86:89]
	v_mfma_f32_16x16x32_bf16 v[82:85], v[166:169], v[150:153], v[82:85]
	v_mfma_f32_16x16x32_bf16 v[78:81], v[174:177], v[142:145], v[78:81]
	v_mfma_f32_16x16x32_bf16 v[74:77], v[174:177], v[150:153], v[74:77]
	v_mfma_f32_16x16x32_bf16 v[70:73], v[182:185], v[142:145], v[70:73]
	v_mfma_f32_16x16x32_bf16 v[66:69], v[182:185], v[150:153], v[66:69]
	v_mfma_f32_16x16x32_bf16 v[216:219], v[162:165], v[146:149], v[94:97]
	v_mfma_f32_16x16x32_bf16 v[220:223], v[162:165], v[154:157], v[90:93]
	v_mfma_f32_16x16x32_bf16 v[224:227], v[170:173], v[146:149], v[86:89]
	v_mfma_f32_16x16x32_bf16 v[228:231], v[170:173], v[154:157], v[82:85]
	v_mfma_f32_16x16x32_bf16 v[232:235], v[178:181], v[146:149], v[78:81]
	v_mfma_f32_16x16x32_bf16 v[236:239], v[178:181], v[154:157], v[74:77]
	v_mfma_f32_16x16x32_bf16 v[142:145], v[186:189], v[146:149], v[70:73]
	v_mfma_f32_16x16x32_bf16 v[146:149], v[186:189], v[154:157], v[66:69]
	s_setprio 0
	s_setprio 3
	v_mfma_f32_16x16x32_bf16 v[66:69], v[158:161], v[190:193], v[126:129]
	v_mfma_f32_16x16x32_bf16 v[150:153], v[162:165], v[194:197], v[66:69]
	v_mfma_f32_16x16x32_bf16 v[66:69], v[158:161], v[198:201], v[122:125]
	v_mfma_f32_16x16x32_bf16 v[154:157], v[162:165], v[202:205], v[66:69]
	v_mfma_f32_16x16x32_bf16 v[66:69], v[166:169], v[190:193], v[118:121]
	v_mfma_f32_16x16x32_bf16 v[158:161], v[170:173], v[194:197], v[66:69]
	v_mfma_f32_16x16x32_bf16 v[66:69], v[166:169], v[198:201], v[114:117]
	v_mfma_f32_16x16x32_bf16 v[162:165], v[170:173], v[202:205], v[66:69]
	v_mfma_f32_16x16x32_bf16 v[66:69], v[174:177], v[190:193], v[110:113]
	v_mfma_f32_16x16x32_bf16 v[166:169], v[178:181], v[194:197], v[66:69]
	v_mfma_f32_16x16x32_bf16 v[66:69], v[174:177], v[198:201], v[106:109]
	v_mfma_f32_16x16x32_bf16 v[170:173], v[178:181], v[202:205], v[66:69]
	v_mfma_f32_16x16x32_bf16 v[66:69], v[182:185], v[190:193], v[102:105]
	v_mfma_f32_16x16x32_bf16 v[174:177], v[186:189], v[194:197], v[66:69]
	v_mfma_f32_16x16x32_bf16 v[66:69], v[182:185], v[198:201], v[98:101]
	v_mfma_f32_16x16x32_bf16 v[178:181], v[186:189], v[202:205], v[66:69]
	s_setprio 0
	s_barrier
	ds_read_b128 v[182:185], v137 offset:32768
	ds_read_b128 v[186:189], v137 offset:33792
	ds_read_b128 v[190:193], v137 offset:34816
	ds_read_b128 v[194:197], v137 offset:35840
	ds_read_b128 v[74:77], v136 offset:32768
	ds_read_b128 v[78:81], v136 offset:33792
	ds_read_b128 v[90:93], v136 offset:34816
	ds_read_b128 v[94:97], v136 offset:35840
	ds_read_b128 v[198:201], v136 offset:36864
	ds_read_b128 v[202:205], v136 offset:37888
	ds_read_b128 v[240:243], v136 offset:38912
	ds_read_b128 v[244:247], v136 offset:39936
	s_waitcnt vmcnt(2)
	s_barrier
	s_waitcnt lgkmcnt(0)
	s_setprio 3
	s_waitcnt lgkmcnt(0)
	v_mfma_f32_16x16x32_bf16 v[30:33], v[74:77], v[182:185], v[30:33]
	v_mfma_f32_16x16x32_bf16 v[26:29], v[74:77], v[190:193], v[26:29]
	v_mfma_f32_16x16x32_bf16 v[22:25], v[90:93], v[182:185], v[22:25]
	v_mfma_f32_16x16x32_bf16 v[18:21], v[90:93], v[190:193], v[18:21]
	v_mfma_f32_16x16x32_bf16 v[14:17], v[198:201], v[182:185], v[14:17]
	v_mfma_f32_16x16x32_bf16 v[10:13], v[198:201], v[190:193], v[10:13]
	v_mfma_f32_16x16x32_bf16 v[6:9], v[240:243], v[182:185], v[6:9]
	v_mfma_f32_16x16x32_bf16 v[2:5], v[240:243], v[190:193], v[2:5]
	v_mfma_f32_16x16x32_bf16 v[118:121], v[78:81], v[186:189], v[30:33]
	v_mfma_f32_16x16x32_bf16 v[114:117], v[78:81], v[194:197], v[26:29]
	v_mfma_f32_16x16x32_bf16 v[102:105], v[94:97], v[186:189], v[22:25]
	v_mfma_f32_16x16x32_bf16 v[98:101], v[94:97], v[194:197], v[18:21]
	v_mfma_f32_16x16x32_bf16 v[86:89], v[202:205], v[186:189], v[14:17]
	v_mfma_f32_16x16x32_bf16 v[82:85], v[202:205], v[194:197], v[10:13]
	v_mfma_f32_16x16x32_bf16 v[70:73], v[244:247], v[186:189], v[6:9]
	v_mfma_f32_16x16x32_bf16 v[66:69], v[244:247], v[194:197], v[2:5]
	s_setprio 0
	s_barrier
	ds_read_b128 v[10:13], v137 offset:49152
	ds_read_b128 v[14:17], v137 offset:50176
	ds_read_b128 v[248:251], v137 offset:51200
	ds_read_b128 v[138:141], v137 offset:52224
	s_waitcnt vmcnt(0)
	s_barrier
	s_waitcnt lgkmcnt(0)
	s_setprio 3
	s_waitcnt lgkmcnt(0)
	v_mfma_f32_16x16x32_bf16 v[2:5], v[74:77], v[10:13], v[62:65]
	v_mfma_f32_16x16x32_bf16 v[126:129], v[78:81], v[14:17], v[2:5]
	v_mfma_f32_16x16x32_bf16 v[2:5], v[74:77], v[248:251], v[58:61]
	v_mfma_f32_16x16x32_bf16 v[122:125], v[78:81], v[138:141], v[2:5]
	v_mfma_f32_16x16x32_bf16 v[2:5], v[90:93], v[10:13], v[54:57]
	v_mfma_f32_16x16x32_bf16 v[110:113], v[94:97], v[14:17], v[2:5]
	v_mfma_f32_16x16x32_bf16 v[2:5], v[90:93], v[248:251], v[50:53]
	v_mfma_f32_16x16x32_bf16 v[106:109], v[94:97], v[138:141], v[2:5]
	v_mfma_f32_16x16x32_bf16 v[2:5], v[198:201], v[10:13], v[46:49]
	v_mfma_f32_16x16x32_bf16 v[94:97], v[202:205], v[14:17], v[2:5]
	v_mfma_f32_16x16x32_bf16 v[2:5], v[198:201], v[248:251], v[42:45]
	v_mfma_f32_16x16x32_bf16 v[90:93], v[202:205], v[138:141], v[2:5]
	v_mfma_f32_16x16x32_bf16 v[2:5], v[240:243], v[10:13], v[38:41]
	v_mfma_f32_16x16x32_bf16 v[78:81], v[244:247], v[14:17], v[2:5]
	v_mfma_f32_16x16x32_bf16 v[2:5], v[240:243], v[248:251], v[34:37]
	v_mfma_f32_16x16x32_bf16 v[74:77], v[244:247], v[138:141], v[2:5]
	s_setprio 0
	s_barrier
	ds_read_b128 v[26:29], v136 offset:49152
	ds_read_b128 v[30:33], v136 offset:50176
	ds_read_b128 v[42:45], v136 offset:51200
	ds_read_b128 v[198:201], v136 offset:52224
	ds_read_b128 v[202:205], v136 offset:53248
	ds_read_b128 v[240:243], v136 offset:54272
	ds_read_b128 v[244:247], v136 offset:55296
	ds_read_b128 v[212:215], v136 offset:56320
	s_barrier
	s_waitcnt lgkmcnt(0)
	s_setprio 3
	s_waitcnt lgkmcnt(0)
	v_mfma_f32_16x16x32_bf16 v[2:5], v[26:29], v[182:185], v[216:219]
	v_mfma_f32_16x16x32_bf16 v[54:57], v[30:33], v[186:189], v[2:5]
	v_mfma_f32_16x16x32_bf16 v[2:5], v[26:29], v[190:193], v[220:223]
	v_mfma_f32_16x16x32_bf16 v[50:53], v[30:33], v[194:197], v[2:5]
	v_mfma_f32_16x16x32_bf16 v[2:5], v[42:45], v[182:185], v[224:227]
	v_mfma_f32_16x16x32_bf16 v[38:41], v[198:201], v[186:189], v[2:5]
	v_mfma_f32_16x16x32_bf16 v[2:5], v[42:45], v[190:193], v[228:231]
	v_mfma_f32_16x16x32_bf16 v[34:37], v[198:201], v[194:197], v[2:5]
	v_mfma_f32_16x16x32_bf16 v[2:5], v[202:205], v[182:185], v[232:235]
	v_mfma_f32_16x16x32_bf16 v[22:25], v[240:243], v[186:189], v[2:5]
	v_mfma_f32_16x16x32_bf16 v[2:5], v[202:205], v[190:193], v[236:239]
	v_mfma_f32_16x16x32_bf16 v[18:21], v[240:243], v[194:197], v[2:5]
	v_mfma_f32_16x16x32_bf16 v[2:5], v[244:247], v[182:185], v[142:145]
	v_mfma_f32_16x16x32_bf16 v[6:9], v[212:215], v[186:189], v[2:5]
	v_mfma_f32_16x16x32_bf16 v[2:5], v[244:247], v[190:193], v[146:149]
	v_mfma_f32_16x16x32_bf16 v[2:5], v[212:215], v[194:197], v[2:5]
	s_setprio 0
	s_setprio 3
	v_mfma_f32_16x16x32_bf16 v[46:49], v[26:29], v[10:13], v[150:153]
	v_mfma_f32_16x16x32_bf16 v[26:29], v[26:29], v[248:251], v[154:157]
	v_mfma_f32_16x16x32_bf16 v[58:61], v[30:33], v[138:141], v[26:29]
	v_mfma_f32_16x16x32_bf16 v[26:29], v[42:45], v[10:13], v[158:161]
	v_mfma_f32_16x16x32_bf16 v[62:65], v[30:33], v[14:17], v[46:49]
	v_mfma_f32_16x16x32_bf16 v[46:49], v[198:201], v[14:17], v[26:29]
	v_mfma_f32_16x16x32_bf16 v[26:29], v[42:45], v[248:251], v[162:165]
	v_mfma_f32_16x16x32_bf16 v[42:45], v[198:201], v[138:141], v[26:29]
	v_mfma_f32_16x16x32_bf16 v[26:29], v[202:205], v[10:13], v[166:169]
	v_mfma_f32_16x16x32_bf16 v[10:13], v[244:247], v[10:13], v[174:177]
	v_mfma_f32_16x16x32_bf16 v[30:33], v[240:243], v[14:17], v[26:29]
	v_mfma_f32_16x16x32_bf16 v[26:29], v[202:205], v[248:251], v[170:173]
	v_mfma_f32_16x16x32_bf16 v[14:17], v[212:215], v[14:17], v[10:13]
	v_mfma_f32_16x16x32_bf16 v[10:13], v[244:247], v[248:251], v[178:181]
	v_mfma_f32_16x16x32_bf16 v[26:29], v[240:243], v[138:141], v[26:29]
	v_mfma_f32_16x16x32_bf16 v[10:13], v[212:215], v[138:141], v[10:13]
	s_setprio 0
	s_and_b64 vcc, exec, s[10:11]
	s_barrier
	s_cbranch_vccz .LBB0_471
	s_barrier
